# P0 weight transposes: fetch phase rewritten (32 row loads in flight, one wait) for 8 of 10 matrices; RWKV consumer hand-written; RG-LRU in producer waves
# speedup vs baseline: 1.0454x; 1.0132x over previous
.LBB0_22:
	s_waitcnt lgkmcnt(0)
	s_sub_i32 s0, 0, s43
	ds_read2_b32 v[44:45], v160 offset0:33 offset1:41
	ds_read2_b32 v[46:47], v160 offset1:8
	ds_read2_b32 v[48:49], v160 offset0:66 offset1:74
	ds_read2_b32 v[50:51], v160 offset0:99 offset1:107
	ds_read2_b32 v[52:53], v160 offset0:132 offset1:140
	ds_read2_b32 v[54:55], v160 offset0:165 offset1:173
	ds_read2_b32 v[56:57], v160 offset0:198 offset1:206
	ds_read2_b32 v[58:59], v160 offset0:231 offset1:239
	s_add_i32 s0, s4, s0
	v_add_u32_e32 v62, s34, v159
	s_ashr_i32 s1, s0, 31
	v_ashrrev_i32_e32 v63, 31, v62
	v_lshl_add_u64 v[60:61], s[0:1], 1, v[38:39]
	v_lshlrev_b64 v[62:63], 11, v[62:63]
	s_waitcnt lgkmcnt(6)
	v_cvt_pk_bf16_f32 v40, v46, v44
	v_lshl_add_u64 v[62:63], v[60:61], 0, v[62:63]
	v_add_u32_e32 v44, s34, v175
	s_waitcnt lgkmcnt(4)
	v_cvt_pk_bf16_f32 v41, v48, v50
	s_waitcnt lgkmcnt(2)
	v_cvt_pk_bf16_f32 v42, v52, v54
	s_waitcnt lgkmcnt(0)
	v_cvt_pk_bf16_f32 v43, v56, v58
	global_store_dwordx4 v[62:63], v[40:43], off
	s_nop 1
	v_cvt_pk_bf16_f32 v40, v47, v45
	v_ashrrev_i32_e32 v45, 31, v44
	v_lshlrev_b64 v[44:45], 11, v[44:45]
	v_cvt_pk_bf16_f32 v41, v49, v51
	v_cvt_pk_bf16_f32 v42, v53, v55
	v_cvt_pk_bf16_f32 v43, v57, v59
	v_lshl_add_u64 v[44:45], v[60:61], 0, v[44:45]
	ds_read2_b32 v[46:47], v160 offset0:16 offset1:24
	ds_read2_b32 v[48:49], v160 offset0:49 offset1:57
	ds_read2_b32 v[50:51], v160 offset0:82 offset1:90
	ds_read2_b32 v[52:53], v160 offset0:115 offset1:123
	ds_read2_b32 v[54:55], v160 offset0:148 offset1:156
	ds_read2_b32 v[56:57], v160 offset0:181 offset1:189
	ds_read2_b32 v[58:59], v160 offset0:214 offset1:222
	ds_read2_b32 v[62:63], v160 offset0:247 offset1:255
	global_store_dwordx4 v[44:45], v[40:43], off
	v_add_u32_e32 v44, s34, v176
	v_ashrrev_i32_e32 v45, 31, v44
	v_lshlrev_b64 v[44:45], 11, v[44:45]
	v_lshl_add_u64 v[44:45], v[60:61], 0, v[44:45]
	s_waitcnt lgkmcnt(6)
	v_cvt_pk_bf16_f32 v40, v46, v48
	s_waitcnt lgkmcnt(4)
	v_cvt_pk_bf16_f32 v41, v50, v52
	s_waitcnt lgkmcnt(2)
	v_cvt_pk_bf16_f32 v42, v54, v56
	s_waitcnt lgkmcnt(0)
	v_cvt_pk_bf16_f32 v43, v58, v62
	global_store_dwordx4 v[44:45], v[40:43], off
	v_add_u32_e32 v44, s34, v177
	v_ashrrev_i32_e32 v45, 31, v44
	v_lshlrev_b64 v[44:45], 11, v[44:45]
	v_lshl_add_u64 v[44:45], v[60:61], 0, v[44:45]
	v_cvt_pk_bf16_f32 v40, v47, v49
	v_cvt_pk_bf16_f32 v41, v51, v53
	v_cvt_pk_bf16_f32 v42, v55, v57
	v_cvt_pk_bf16_f32 v43, v59, v63
	global_store_dwordx4 v[44:45], v[40:43], off
	s_waitcnt lgkmcnt(0)

.LBB0_37:
	s_andn2_b64 vcc, exec, s[0:1]
	s_cbranch_vccnz .LBB0_39
	s_and_b32 s1, s4, 0x3c0
	s_and_b32 s0, s12, 0x1ffe0
	s_lshl_b32 s34, s0, 2
	v_lshl_add_u64 v[40:41], v[8:9], 0, s[34:35]
	v_add_u32_e32 v62, s0, v159
	s_lshl_b32 s34, s1, 1
	v_ashrrev_i32_e32 v63, 31, v62
	v_lshlrev_b64 v[62:63], 11, v[62:63]
	v_add_u32_e32 v232, s1, v65
	s_mov_b32 s98, 0x1000
	v_and_b32_e32 v237, 31, v64
	v_mul_u32_u24_e32 v236, 33, v65
	v_add_lshl_u32 v236, v236, v237, 2
	s_lshl_b32 s99, s33, 14
	v_add_u32_e32 v236, s99, v236
	v_mad_i64_i32 v[234:235], s[100:101], v232, s98, v[40:41]
	global_load_dword v200, v[234:235], off
	v_add_u32_e32 v232, 2, v232
	v_mad_i64_i32 v[234:235], s[100:101], v232, s98, v[40:41]
	global_load_dword v201, v[234:235], off
	v_add_u32_e32 v232, 2, v232
	v_mad_i64_i32 v[234:235], s[100:101], v232, s98, v[40:41]
	global_load_dword v202, v[234:235], off
	v_add_u32_e32 v232, 2, v232
	v_mad_i64_i32 v[234:235], s[100:101], v232, s98, v[40:41]
	global_load_dword v203, v[234:235], off
	v_add_u32_e32 v232, 2, v232
	v_mad_i64_i32 v[234:235], s[100:101], v232, s98, v[40:41]
	global_load_dword v204, v[234:235], off
	v_add_u32_e32 v232, 2, v232
	v_mad_i64_i32 v[234:235], s[100:101], v232, s98, v[40:41]
	global_load_dword v205, v[234:235], off
	v_add_u32_e32 v232, 2, v232
	v_mad_i64_i32 v[234:235], s[100:101], v232, s98, v[40:41]
	global_load_dword v206, v[234:235], off
	v_add_u32_e32 v232, 2, v232
	v_mad_i64_i32 v[234:235], s[100:101], v232, s98, v[40:41]
	global_load_dword v207, v[234:235], off
	v_add_u32_e32 v232, 2, v232
	v_mad_i64_i32 v[234:235], s[100:101], v232, s98, v[40:41]
	global_load_dword v208, v[234:235], off
	v_add_u32_e32 v232, 2, v232
	v_mad_i64_i32 v[234:235], s[100:101], v232, s98, v[40:41]
	global_load_dword v209, v[234:235], off
	v_add_u32_e32 v232, 2, v232
	v_mad_i64_i32 v[234:235], s[100:101], v232, s98, v[40:41]
	global_load_dword v210, v[234:235], off
	v_add_u32_e32 v232, 2, v232
	v_mad_i64_i32 v[234:235], s[100:101], v232, s98, v[40:41]
	global_load_dword v211, v[234:235], off
	v_add_u32_e32 v232, 2, v232
	v_mad_i64_i32 v[234:235], s[100:101], v232, s98, v[40:41]
	global_load_dword v212, v[234:235], off
	v_add_u32_e32 v232, 2, v232
	v_mad_i64_i32 v[234:235], s[100:101], v232, s98, v[40:41]
	global_load_dword v213, v[234:235], off
	v_add_u32_e32 v232, 2, v232
	v_mad_i64_i32 v[234:235], s[100:101], v232, s98, v[40:41]
	global_load_dword v214, v[234:235], off
	v_add_u32_e32 v232, 2, v232
	v_mad_i64_i32 v[234:235], s[100:101], v232, s98, v[40:41]
	global_load_dword v215, v[234:235], off
	v_add_u32_e32 v232, 2, v232
	v_mad_i64_i32 v[234:235], s[100:101], v232, s98, v[40:41]
	global_load_dword v216, v[234:235], off
	v_add_u32_e32 v232, 2, v232
	v_mad_i64_i32 v[234:235], s[100:101], v232, s98, v[40:41]
	global_load_dword v217, v[234:235], off
	v_add_u32_e32 v232, 2, v232
	v_mad_i64_i32 v[234:235], s[100:101], v232, s98, v[40:41]
	global_load_dword v218, v[234:235], off
	v_add_u32_e32 v232, 2, v232
	v_mad_i64_i32 v[234:235], s[100:101], v232, s98, v[40:41]
	global_load_dword v219, v[234:235], off
	v_add_u32_e32 v232, 2, v232
	v_mad_i64_i32 v[234:235], s[100:101], v232, s98, v[40:41]
	global_load_dword v220, v[234:235], off
	v_add_u32_e32 v232, 2, v232
	v_mad_i64_i32 v[234:235], s[100:101], v232, s98, v[40:41]
	global_load_dword v221, v[234:235], off
	v_add_u32_e32 v232, 2, v232
	v_mad_i64_i32 v[234:235], s[100:101], v232, s98, v[40:41]
	global_load_dword v222, v[234:235], off
	v_add_u32_e32 v232, 2, v232
	v_mad_i64_i32 v[234:235], s[100:101], v232, s98, v[40:41]
	global_load_dword v223, v[234:235], off
	v_add_u32_e32 v232, 2, v232
	v_mad_i64_i32 v[234:235], s[100:101], v232, s98, v[40:41]
	global_load_dword v224, v[234:235], off
	v_add_u32_e32 v232, 2, v232
	v_mad_i64_i32 v[234:235], s[100:101], v232, s98, v[40:41]
	global_load_dword v225, v[234:235], off
	v_add_u32_e32 v232, 2, v232
	v_mad_i64_i32 v[234:235], s[100:101], v232, s98, v[40:41]
	global_load_dword v226, v[234:235], off
	v_add_u32_e32 v232, 2, v232
	v_mad_i64_i32 v[234:235], s[100:101], v232, s98, v[40:41]
	global_load_dword v227, v[234:235], off
	v_add_u32_e32 v232, 2, v232
	v_mad_i64_i32 v[234:235], s[100:101], v232, s98, v[40:41]
	global_load_dword v228, v[234:235], off
	v_add_u32_e32 v232, 2, v232
	v_mad_i64_i32 v[234:235], s[100:101], v232, s98, v[40:41]
	global_load_dword v229, v[234:235], off
	v_add_u32_e32 v232, 2, v232
	v_mad_i64_i32 v[234:235], s[100:101], v232, s98, v[40:41]
	global_load_dword v230, v[234:235], off
	v_add_u32_e32 v232, 2, v232
	v_mad_i64_i32 v[234:235], s[100:101], v232, s98, v[40:41]
	global_load_dword v231, v[234:235], off
	s_waitcnt vmcnt(0)
	ds_write_b32 v236, v200 offset:0
	ds_write_b32 v236, v201 offset:264
	ds_write_b32 v236, v202 offset:528
	ds_write_b32 v236, v203 offset:792
	ds_write_b32 v236, v204 offset:1056
	ds_write_b32 v236, v205 offset:1320
	ds_write_b32 v236, v206 offset:1584
	ds_write_b32 v236, v207 offset:1848
	ds_write_b32 v236, v208 offset:2112
	ds_write_b32 v236, v209 offset:2376
	ds_write_b32 v236, v210 offset:2640
	ds_write_b32 v236, v211 offset:2904
	ds_write_b32 v236, v212 offset:3168
	ds_write_b32 v236, v213 offset:3432
	ds_write_b32 v236, v214 offset:3696
	ds_write_b32 v236, v215 offset:3960
	ds_write_b32 v236, v216 offset:4224
	ds_write_b32 v236, v217 offset:4488
	ds_write_b32 v236, v218 offset:4752
	ds_write_b32 v236, v219 offset:5016
	ds_write_b32 v236, v220 offset:5280
	ds_write_b32 v236, v221 offset:5544
	ds_write_b32 v236, v222 offset:5808
	ds_write_b32 v236, v223 offset:6072
	ds_write_b32 v236, v224 offset:6336
	ds_write_b32 v236, v225 offset:6600
	ds_write_b32 v236, v226 offset:6864
	ds_write_b32 v236, v227 offset:7128
	ds_write_b32 v236, v228 offset:7392
	ds_write_b32 v236, v229 offset:7656
	ds_write_b32 v236, v230 offset:7920
	ds_write_b32 v236, v231 offset:8184
	s_waitcnt lgkmcnt(0)
	ds_read2_b32 v[46:47], v160 offset0:33 offset1:41
	ds_read2_b32 v[48:49], v160 offset1:8
	ds_read2_b32 v[50:51], v160 offset0:66 offset1:74
	ds_read2_b32 v[52:53], v160 offset0:99 offset1:107
	ds_read2_b32 v[54:55], v160 offset0:132 offset1:140
	ds_read2_b32 v[56:57], v160 offset0:165 offset1:173
	ds_read2_b32 v[58:59], v160 offset0:198 offset1:206
	ds_read2_b32 v[60:61], v160 offset0:231 offset1:239
	v_lshl_add_u64 v[44:45], v[26:27], 0, s[34:35]
	s_waitcnt lgkmcnt(6)
	v_cvt_pk_bf16_f32 v40, v48, v46
	v_lshl_add_u64 v[62:63], v[44:45], 0, v[62:63]
	v_add_u32_e32 v46, s0, v175
	s_waitcnt lgkmcnt(4)
	v_cvt_pk_bf16_f32 v41, v50, v52
	s_waitcnt lgkmcnt(2)
	v_cvt_pk_bf16_f32 v42, v54, v56
	s_waitcnt lgkmcnt(0)
	v_cvt_pk_bf16_f32 v43, v58, v60
	global_store_dwordx4 v[62:63], v[40:43], off
	v_add_u32_e32 v62, s0, v176
	v_ashrrev_i32_e32 v63, 31, v62
	v_cvt_pk_bf16_f32 v40, v49, v47
	v_ashrrev_i32_e32 v47, 31, v46
	v_lshlrev_b64 v[46:47], 11, v[46:47]
	v_lshl_add_u64 v[46:47], v[44:45], 0, v[46:47]
	v_cvt_pk_bf16_f32 v41, v51, v53
	v_cvt_pk_bf16_f32 v42, v55, v57
	v_cvt_pk_bf16_f32 v43, v59, v61
	global_store_dwordx4 v[46:47], v[40:43], off
	ds_read2_b32 v[46:47], v160 offset0:16 offset1:24
	ds_read2_b32 v[48:49], v160 offset0:49 offset1:57
	ds_read2_b32 v[50:51], v160 offset0:82 offset1:90
	ds_read2_b32 v[52:53], v160 offset0:115 offset1:123
	ds_read2_b32 v[54:55], v160 offset0:148 offset1:156
	ds_read2_b32 v[56:57], v160 offset0:181 offset1:189
	ds_read2_b32 v[58:59], v160 offset0:214 offset1:222
	ds_read2_b32 v[60:61], v160 offset0:247 offset1:255
	v_lshlrev_b64 v[62:63], 11, v[62:63]
	s_waitcnt lgkmcnt(6)
	v_cvt_pk_bf16_f32 v40, v46, v48
	v_lshl_add_u64 v[62:63], v[44:45], 0, v[62:63]
	v_add_u32_e32 v46, s0, v177
	s_waitcnt lgkmcnt(4)
	v_cvt_pk_bf16_f32 v41, v50, v52
	s_waitcnt lgkmcnt(2)
	v_cvt_pk_bf16_f32 v42, v54, v56
	s_waitcnt lgkmcnt(0)
	v_cvt_pk_bf16_f32 v43, v58, v60
	global_store_dwordx4 v[62:63], v[40:43], off
	s_nop 1
	v_cvt_pk_bf16_f32 v40, v47, v49
	v_ashrrev_i32_e32 v47, 31, v46
	v_lshlrev_b64 v[46:47], 11, v[46:47]
	v_lshl_add_u64 v[44:45], v[44:45], 0, v[46:47]
	v_cvt_pk_bf16_f32 v41, v51, v53
	v_cvt_pk_bf16_f32 v42, v55, v57
	v_cvt_pk_bf16_f32 v43, v59, v61
	global_store_dwordx4 v[44:45], v[40:43], off
	s_waitcnt lgkmcnt(0)

.LBB0_40:
	s_andn2_b64 vcc, exec, s[0:1]
	s_cbranch_vccnz .LBB0_42
	s_add_i32 s0, s12, 0x400
	s_and_b32 s0, s0, 0x1ffe0
	s_and_b32 s1, s4, 0x3c0
	s_lshl_b32 s34, s0, 2
	s_add_u32 s52, s14, s34
	s_addc_u32 s53, s15, 0
	v_lshl_add_u64 v[40:41], s[52:53], 0, v[0:1]
	s_mov_b64 s[52:53], 0x1000
	v_lshl_add_u64 v[40:41], v[40:41], 0, s[52:53]
	v_add_u32_e32 v62, s0, v159
	s_lshl_b32 s34, s1, 1
	v_ashrrev_i32_e32 v63, 31, v62
	v_lshlrev_b64 v[62:63], 11, v[62:63]
	v_add_u32_e32 v232, s1, v65
	s_mov_b32 s98, 0x2000
	v_and_b32_e32 v237, 31, v64
	v_mul_u32_u24_e32 v236, 33, v65
	v_add_lshl_u32 v236, v236, v237, 2
	s_lshl_b32 s99, s33, 14
	v_add_u32_e32 v236, s99, v236
	v_mad_i64_i32 v[234:235], s[100:101], v232, s98, v[40:41]
	global_load_dword v200, v[234:235], off
	v_add_u32_e32 v232, 2, v232
	v_mad_i64_i32 v[234:235], s[100:101], v232, s98, v[40:41]
	global_load_dword v201, v[234:235], off
	v_add_u32_e32 v232, 2, v232
	v_mad_i64_i32 v[234:235], s[100:101], v232, s98, v[40:41]
	global_load_dword v202, v[234:235], off
	v_add_u32_e32 v232, 2, v232
	v_mad_i64_i32 v[234:235], s[100:101], v232, s98, v[40:41]
	global_load_dword v203, v[234:235], off
	v_add_u32_e32 v232, 2, v232
	v_mad_i64_i32 v[234:235], s[100:101], v232, s98, v[40:41]
	global_load_dword v204, v[234:235], off
	v_add_u32_e32 v232, 2, v232
	v_mad_i64_i32 v[234:235], s[100:101], v232, s98, v[40:41]
	global_load_dword v205, v[234:235], off
	v_add_u32_e32 v232, 2, v232
	v_mad_i64_i32 v[234:235], s[100:101], v232, s98, v[40:41]
	global_load_dword v206, v[234:235], off
	v_add_u32_e32 v232, 2, v232
	v_mad_i64_i32 v[234:235], s[100:101], v232, s98, v[40:41]
	global_load_dword v207, v[234:235], off
	v_add_u32_e32 v232, 2, v232
	v_mad_i64_i32 v[234:235], s[100:101], v232, s98, v[40:41]
	global_load_dword v208, v[234:235], off
	v_add_u32_e32 v232, 2, v232
	v_mad_i64_i32 v[234:235], s[100:101], v232, s98, v[40:41]
	global_load_dword v209, v[234:235], off
	v_add_u32_e32 v232, 2, v232
	v_mad_i64_i32 v[234:235], s[100:101], v232, s98, v[40:41]
	global_load_dword v210, v[234:235], off
	v_add_u32_e32 v232, 2, v232
	v_mad_i64_i32 v[234:235], s[100:101], v232, s98, v[40:41]
	global_load_dword v211, v[234:235], off
	v_add_u32_e32 v232, 2, v232
	v_mad_i64_i32 v[234:235], s[100:101], v232, s98, v[40:41]
	global_load_dword v212, v[234:235], off
	v_add_u32_e32 v232, 2, v232
	v_mad_i64_i32 v[234:235], s[100:101], v232, s98, v[40:41]
	global_load_dword v213, v[234:235], off
	v_add_u32_e32 v232, 2, v232
	v_mad_i64_i32 v[234:235], s[100:101], v232, s98, v[40:41]
	global_load_dword v214, v[234:235], off
	v_add_u32_e32 v232, 2, v232
	v_mad_i64_i32 v[234:235], s[100:101], v232, s98, v[40:41]
	global_load_dword v215, v[234:235], off
	v_add_u32_e32 v232, 2, v232
	v_mad_i64_i32 v[234:235], s[100:101], v232, s98, v[40:41]
	global_load_dword v216, v[234:235], off
	v_add_u32_e32 v232, 2, v232
	v_mad_i64_i32 v[234:235], s[100:101], v232, s98, v[40:41]
	global_load_dword v217, v[234:235], off
	v_add_u32_e32 v232, 2, v232
	v_mad_i64_i32 v[234:235], s[100:101], v232, s98, v[40:41]
	global_load_dword v218, v[234:235], off
	v_add_u32_e32 v232, 2, v232
	v_mad_i64_i32 v[234:235], s[100:101], v232, s98, v[40:41]
	global_load_dword v219, v[234:235], off
	v_add_u32_e32 v232, 2, v232
	v_mad_i64_i32 v[234:235], s[100:101], v232, s98, v[40:41]
	global_load_dword v220, v[234:235], off
	v_add_u32_e32 v232, 2, v232
	v_mad_i64_i32 v[234:235], s[100:101], v232, s98, v[40:41]
	global_load_dword v221, v[234:235], off
	v_add_u32_e32 v232, 2, v232
	v_mad_i64_i32 v[234:235], s[100:101], v232, s98, v[40:41]
	global_load_dword v222, v[234:235], off
	v_add_u32_e32 v232, 2, v232
	v_mad_i64_i32 v[234:235], s[100:101], v232, s98, v[40:41]
	global_load_dword v223, v[234:235], off
	v_add_u32_e32 v232, 2, v232
	v_mad_i64_i32 v[234:235], s[100:101], v232, s98, v[40:41]
	global_load_dword v224, v[234:235], off
	v_add_u32_e32 v232, 2, v232
	v_mad_i64_i32 v[234:235], s[100:101], v232, s98, v[40:41]
	global_load_dword v225, v[234:235], off
	v_add_u32_e32 v232, 2, v232
	v_mad_i64_i32 v[234:235], s[100:101], v232, s98, v[40:41]
	global_load_dword v226, v[234:235], off
	v_add_u32_e32 v232, 2, v232
	v_mad_i64_i32 v[234:235], s[100:101], v232, s98, v[40:41]
	global_load_dword v227, v[234:235], off
	v_add_u32_e32 v232, 2, v232
	v_mad_i64_i32 v[234:235], s[100:101], v232, s98, v[40:41]
	global_load_dword v228, v[234:235], off
	v_add_u32_e32 v232, 2, v232
	v_mad_i64_i32 v[234:235], s[100:101], v232, s98, v[40:41]
	global_load_dword v229, v[234:235], off
	v_add_u32_e32 v232, 2, v232
	v_mad_i64_i32 v[234:235], s[100:101], v232, s98, v[40:41]
	global_load_dword v230, v[234:235], off
	v_add_u32_e32 v232, 2, v232
	v_mad_i64_i32 v[234:235], s[100:101], v232, s98, v[40:41]
	global_load_dword v231, v[234:235], off
	s_waitcnt vmcnt(0)
	ds_write_b32 v236, v200 offset:0
	ds_write_b32 v236, v201 offset:264
	ds_write_b32 v236, v202 offset:528
	ds_write_b32 v236, v203 offset:792
	ds_write_b32 v236, v204 offset:1056
	ds_write_b32 v236, v205 offset:1320
	ds_write_b32 v236, v206 offset:1584
	ds_write_b32 v236, v207 offset:1848
	ds_write_b32 v236, v208 offset:2112
	ds_write_b32 v236, v209 offset:2376
	ds_write_b32 v236, v210 offset:2640
	ds_write_b32 v236, v211 offset:2904
	ds_write_b32 v236, v212 offset:3168
	ds_write_b32 v236, v213 offset:3432
	ds_write_b32 v236, v214 offset:3696
	ds_write_b32 v236, v215 offset:3960
	ds_write_b32 v236, v216 offset:4224
	ds_write_b32 v236, v217 offset:4488
	ds_write_b32 v236, v218 offset:4752
	ds_write_b32 v236, v219 offset:5016
	ds_write_b32 v236, v220 offset:5280
	ds_write_b32 v236, v221 offset:5544
	ds_write_b32 v236, v222 offset:5808
	ds_write_b32 v236, v223 offset:6072
	ds_write_b32 v236, v224 offset:6336
	ds_write_b32 v236, v225 offset:6600
	ds_write_b32 v236, v226 offset:6864
	ds_write_b32 v236, v227 offset:7128
	ds_write_b32 v236, v228 offset:7392
	ds_write_b32 v236, v229 offset:7656
	ds_write_b32 v236, v230 offset:7920
	ds_write_b32 v236, v231 offset:8184
	s_waitcnt lgkmcnt(0)
	ds_read2_b32 v[46:47], v160 offset0:33 offset1:41
	ds_read2_b32 v[48:49], v160 offset1:8
	ds_read2_b32 v[50:51], v160 offset0:66 offset1:74
	ds_read2_b32 v[52:53], v160 offset0:99 offset1:107
	ds_read2_b32 v[54:55], v160 offset0:132 offset1:140
	ds_read2_b32 v[56:57], v160 offset0:165 offset1:173
	ds_read2_b32 v[58:59], v160 offset0:198 offset1:206
	ds_read2_b32 v[60:61], v160 offset0:231 offset1:239
	v_lshl_add_u64 v[44:45], v[28:29], 0, s[34:35]
	s_waitcnt lgkmcnt(6)
	v_cvt_pk_bf16_f32 v40, v48, v46
	v_lshl_add_u64 v[62:63], v[44:45], 0, v[62:63]
	v_add_u32_e32 v46, s0, v175
	s_waitcnt lgkmcnt(4)
	v_cvt_pk_bf16_f32 v41, v50, v52
	s_waitcnt lgkmcnt(2)
	v_cvt_pk_bf16_f32 v42, v54, v56
	s_waitcnt lgkmcnt(0)
	v_cvt_pk_bf16_f32 v43, v58, v60
	global_store_dwordx4 v[62:63], v[40:43], off
	v_add_u32_e32 v62, s0, v176
	v_ashrrev_i32_e32 v63, 31, v62
	v_cvt_pk_bf16_f32 v40, v49, v47
	v_ashrrev_i32_e32 v47, 31, v46
	v_lshlrev_b64 v[46:47], 11, v[46:47]
	v_lshl_add_u64 v[46:47], v[44:45], 0, v[46:47]
	v_cvt_pk_bf16_f32 v41, v51, v53
	v_cvt_pk_bf16_f32 v42, v55, v57
	v_cvt_pk_bf16_f32 v43, v59, v61
	global_store_dwordx4 v[46:47], v[40:43], off
	ds_read2_b32 v[46:47], v160 offset0:16 offset1:24
	ds_read2_b32 v[48:49], v160 offset0:49 offset1:57
	ds_read2_b32 v[50:51], v160 offset0:82 offset1:90
	ds_read2_b32 v[52:53], v160 offset0:115 offset1:123
	ds_read2_b32 v[54:55], v160 offset0:148 offset1:156
	ds_read2_b32 v[56:57], v160 offset0:181 offset1:189
	ds_read2_b32 v[58:59], v160 offset0:214 offset1:222
	ds_read2_b32 v[60:61], v160 offset0:247 offset1:255
	v_lshlrev_b64 v[62:63], 11, v[62:63]
	s_waitcnt lgkmcnt(6)
	v_cvt_pk_bf16_f32 v40, v46, v48
	v_lshl_add_u64 v[62:63], v[44:45], 0, v[62:63]
	v_add_u32_e32 v46, s0, v177
	s_waitcnt lgkmcnt(4)
	v_cvt_pk_bf16_f32 v41, v50, v52
	s_waitcnt lgkmcnt(2)
	v_cvt_pk_bf16_f32 v42, v54, v56
	s_waitcnt lgkmcnt(0)
	v_cvt_pk_bf16_f32 v43, v58, v60
	global_store_dwordx4 v[62:63], v[40:43], off
	s_nop 1
	v_cvt_pk_bf16_f32 v40, v47, v49
	v_ashrrev_i32_e32 v47, 31, v46
	v_lshlrev_b64 v[46:47], 11, v[46:47]
	v_lshl_add_u64 v[44:45], v[44:45], 0, v[46:47]
	v_cvt_pk_bf16_f32 v41, v51, v53
	v_cvt_pk_bf16_f32 v42, v55, v57
	v_cvt_pk_bf16_f32 v43, v59, v61
	global_store_dwordx4 v[44:45], v[40:43], off
	s_waitcnt lgkmcnt(0)

.LBB0_43:
	s_andn2_b64 vcc, exec, s[0:1]
	s_cbranch_vccnz .LBB0_45
	s_and_b32 s1, s4, 0x3c0
	s_add_i32 s0, s12, 0x800
	s_and_b32 s0, s0, 0x1ffe0
	s_lshl_b32 s34, s0, 2
	v_lshl_add_u64 v[40:41], v[10:11], 0, s[34:35]
	v_add_u32_e32 v62, s0, v159
	s_lshl_b32 s34, s1, 1
	v_ashrrev_i32_e32 v63, 31, v62
	v_lshlrev_b64 v[62:63], 11, v[62:63]
	v_add_u32_e32 v232, s1, v65
	s_mov_b32 s98, 0x2000
	v_and_b32_e32 v237, 31, v64
	v_mul_u32_u24_e32 v236, 33, v65
	v_add_lshl_u32 v236, v236, v237, 2
	s_lshl_b32 s99, s33, 14
	v_add_u32_e32 v236, s99, v236
	v_mad_i64_i32 v[234:235], s[100:101], v232, s98, v[40:41]
	global_load_dword v200, v[234:235], off
	v_add_u32_e32 v232, 2, v232
	v_mad_i64_i32 v[234:235], s[100:101], v232, s98, v[40:41]
	global_load_dword v201, v[234:235], off
	v_add_u32_e32 v232, 2, v232
	v_mad_i64_i32 v[234:235], s[100:101], v232, s98, v[40:41]
	global_load_dword v202, v[234:235], off
	v_add_u32_e32 v232, 2, v232
	v_mad_i64_i32 v[234:235], s[100:101], v232, s98, v[40:41]
	global_load_dword v203, v[234:235], off
	v_add_u32_e32 v232, 2, v232
	v_mad_i64_i32 v[234:235], s[100:101], v232, s98, v[40:41]
	global_load_dword v204, v[234:235], off
	v_add_u32_e32 v232, 2, v232
	v_mad_i64_i32 v[234:235], s[100:101], v232, s98, v[40:41]
	global_load_dword v205, v[234:235], off
	v_add_u32_e32 v232, 2, v232
	v_mad_i64_i32 v[234:235], s[100:101], v232, s98, v[40:41]
	global_load_dword v206, v[234:235], off
	v_add_u32_e32 v232, 2, v232
	v_mad_i64_i32 v[234:235], s[100:101], v232, s98, v[40:41]
	global_load_dword v207, v[234:235], off
	v_add_u32_e32 v232, 2, v232
	v_mad_i64_i32 v[234:235], s[100:101], v232, s98, v[40:41]
	global_load_dword v208, v[234:235], off
	v_add_u32_e32 v232, 2, v232
	v_mad_i64_i32 v[234:235], s[100:101], v232, s98, v[40:41]
	global_load_dword v209, v[234:235], off
	v_add_u32_e32 v232, 2, v232
	v_mad_i64_i32 v[234:235], s[100:101], v232, s98, v[40:41]
	global_load_dword v210, v[234:235], off
	v_add_u32_e32 v232, 2, v232
	v_mad_i64_i32 v[234:235], s[100:101], v232, s98, v[40:41]
	global_load_dword v211, v[234:235], off
	v_add_u32_e32 v232, 2, v232
	v_mad_i64_i32 v[234:235], s[100:101], v232, s98, v[40:41]
	global_load_dword v212, v[234:235], off
	v_add_u32_e32 v232, 2, v232
	v_mad_i64_i32 v[234:235], s[100:101], v232, s98, v[40:41]
	global_load_dword v213, v[234:235], off
	v_add_u32_e32 v232, 2, v232
	v_mad_i64_i32 v[234:235], s[100:101], v232, s98, v[40:41]
	global_load_dword v214, v[234:235], off
	v_add_u32_e32 v232, 2, v232
	v_mad_i64_i32 v[234:235], s[100:101], v232, s98, v[40:41]
	global_load_dword v215, v[234:235], off
	v_add_u32_e32 v232, 2, v232
	v_mad_i64_i32 v[234:235], s[100:101], v232, s98, v[40:41]
	global_load_dword v216, v[234:235], off
	v_add_u32_e32 v232, 2, v232
	v_mad_i64_i32 v[234:235], s[100:101], v232, s98, v[40:41]
	global_load_dword v217, v[234:235], off
	v_add_u32_e32 v232, 2, v232
	v_mad_i64_i32 v[234:235], s[100:101], v232, s98, v[40:41]
	global_load_dword v218, v[234:235], off
	v_add_u32_e32 v232, 2, v232
	v_mad_i64_i32 v[234:235], s[100:101], v232, s98, v[40:41]
	global_load_dword v219, v[234:235], off
	v_add_u32_e32 v232, 2, v232
	v_mad_i64_i32 v[234:235], s[100:101], v232, s98, v[40:41]
	global_load_dword v220, v[234:235], off
	v_add_u32_e32 v232, 2, v232
	v_mad_i64_i32 v[234:235], s[100:101], v232, s98, v[40:41]
	global_load_dword v221, v[234:235], off
	v_add_u32_e32 v232, 2, v232
	v_mad_i64_i32 v[234:235], s[100:101], v232, s98, v[40:41]
	global_load_dword v222, v[234:235], off
	v_add_u32_e32 v232, 2, v232
	v_mad_i64_i32 v[234:235], s[100:101], v232, s98, v[40:41]
	global_load_dword v223, v[234:235], off
	v_add_u32_e32 v232, 2, v232
	v_mad_i64_i32 v[234:235], s[100:101], v232, s98, v[40:41]
	global_load_dword v224, v[234:235], off
	v_add_u32_e32 v232, 2, v232
	v_mad_i64_i32 v[234:235], s[100:101], v232, s98, v[40:41]
	global_load_dword v225, v[234:235], off
	v_add_u32_e32 v232, 2, v232
	v_mad_i64_i32 v[234:235], s[100:101], v232, s98, v[40:41]
	global_load_dword v226, v[234:235], off
	v_add_u32_e32 v232, 2, v232
	v_mad_i64_i32 v[234:235], s[100:101], v232, s98, v[40:41]
	global_load_dword v227, v[234:235], off
	v_add_u32_e32 v232, 2, v232
	v_mad_i64_i32 v[234:235], s[100:101], v232, s98, v[40:41]
	global_load_dword v228, v[234:235], off
	v_add_u32_e32 v232, 2, v232
	v_mad_i64_i32 v[234:235], s[100:101], v232, s98, v[40:41]
	global_load_dword v229, v[234:235], off
	v_add_u32_e32 v232, 2, v232
	v_mad_i64_i32 v[234:235], s[100:101], v232, s98, v[40:41]
	global_load_dword v230, v[234:235], off
	v_add_u32_e32 v232, 2, v232
	v_mad_i64_i32 v[234:235], s[100:101], v232, s98, v[40:41]
	global_load_dword v231, v[234:235], off
	s_waitcnt vmcnt(0)
	ds_write_b32 v236, v200 offset:0
	ds_write_b32 v236, v201 offset:264
	ds_write_b32 v236, v202 offset:528
	ds_write_b32 v236, v203 offset:792
	ds_write_b32 v236, v204 offset:1056
	ds_write_b32 v236, v205 offset:1320
	ds_write_b32 v236, v206 offset:1584
	ds_write_b32 v236, v207 offset:1848
	ds_write_b32 v236, v208 offset:2112
	ds_write_b32 v236, v209 offset:2376
	ds_write_b32 v236, v210 offset:2640
	ds_write_b32 v236, v211 offset:2904
	ds_write_b32 v236, v212 offset:3168
	ds_write_b32 v236, v213 offset:3432
	ds_write_b32 v236, v214 offset:3696
	ds_write_b32 v236, v215 offset:3960
	ds_write_b32 v236, v216 offset:4224
	ds_write_b32 v236, v217 offset:4488
	ds_write_b32 v236, v218 offset:4752
	ds_write_b32 v236, v219 offset:5016
	ds_write_b32 v236, v220 offset:5280
	ds_write_b32 v236, v221 offset:5544
	ds_write_b32 v236, v222 offset:5808
	ds_write_b32 v236, v223 offset:6072
	ds_write_b32 v236, v224 offset:6336
	ds_write_b32 v236, v225 offset:6600
	ds_write_b32 v236, v226 offset:6864
	ds_write_b32 v236, v227 offset:7128
	ds_write_b32 v236, v228 offset:7392
	ds_write_b32 v236, v229 offset:7656
	ds_write_b32 v236, v230 offset:7920
	ds_write_b32 v236, v231 offset:8184
	s_waitcnt lgkmcnt(0)
	ds_read2_b32 v[46:47], v160 offset0:33 offset1:41
	ds_read2_b32 v[48:49], v160 offset1:8
	ds_read2_b32 v[50:51], v160 offset0:66 offset1:74
	ds_read2_b32 v[52:53], v160 offset0:99 offset1:107
	ds_read2_b32 v[54:55], v160 offset0:132 offset1:140
	ds_read2_b32 v[56:57], v160 offset0:165 offset1:173
	ds_read2_b32 v[58:59], v160 offset0:198 offset1:206
	ds_read2_b32 v[60:61], v160 offset0:231 offset1:239
	v_lshl_add_u64 v[44:45], v[30:31], 0, s[34:35]
	s_waitcnt lgkmcnt(6)
	v_cvt_pk_bf16_f32 v40, v48, v46
	v_lshl_add_u64 v[62:63], v[44:45], 0, v[62:63]
	v_add_u32_e32 v46, s0, v175
	s_waitcnt lgkmcnt(4)
	v_cvt_pk_bf16_f32 v41, v50, v52
	s_waitcnt lgkmcnt(2)
	v_cvt_pk_bf16_f32 v42, v54, v56
	s_waitcnt lgkmcnt(0)
	v_cvt_pk_bf16_f32 v43, v58, v60
	global_store_dwordx4 v[62:63], v[40:43], off
	v_add_u32_e32 v62, s0, v176
	v_ashrrev_i32_e32 v63, 31, v62
	v_cvt_pk_bf16_f32 v40, v49, v47
	v_ashrrev_i32_e32 v47, 31, v46
	v_lshlrev_b64 v[46:47], 11, v[46:47]
	v_lshl_add_u64 v[46:47], v[44:45], 0, v[46:47]
	v_cvt_pk_bf16_f32 v41, v51, v53
	v_cvt_pk_bf16_f32 v42, v55, v57
	v_cvt_pk_bf16_f32 v43, v59, v61
	global_store_dwordx4 v[46:47], v[40:43], off
	ds_read2_b32 v[46:47], v160 offset0:16 offset1:24
	ds_read2_b32 v[48:49], v160 offset0:49 offset1:57
	ds_read2_b32 v[50:51], v160 offset0:82 offset1:90
	ds_read2_b32 v[52:53], v160 offset0:115 offset1:123
	ds_read2_b32 v[54:55], v160 offset0:148 offset1:156
	ds_read2_b32 v[56:57], v160 offset0:181 offset1:189
	ds_read2_b32 v[58:59], v160 offset0:214 offset1:222
	ds_read2_b32 v[60:61], v160 offset0:247 offset1:255
	v_lshlrev_b64 v[62:63], 11, v[62:63]
	s_waitcnt lgkmcnt(6)
	v_cvt_pk_bf16_f32 v40, v46, v48
	v_lshl_add_u64 v[62:63], v[44:45], 0, v[62:63]
	v_add_u32_e32 v46, s0, v177
	s_waitcnt lgkmcnt(4)
	v_cvt_pk_bf16_f32 v41, v50, v52
	s_waitcnt lgkmcnt(2)
	v_cvt_pk_bf16_f32 v42, v54, v56
	s_waitcnt lgkmcnt(0)
	v_cvt_pk_bf16_f32 v43, v58, v60
	global_store_dwordx4 v[62:63], v[40:43], off
	s_nop 1
	v_cvt_pk_bf16_f32 v40, v47, v49
	v_ashrrev_i32_e32 v47, 31, v46
	v_lshlrev_b64 v[46:47], 11, v[46:47]
	v_lshl_add_u64 v[44:45], v[44:45], 0, v[46:47]
	v_cvt_pk_bf16_f32 v41, v51, v53
	v_cvt_pk_bf16_f32 v42, v55, v57
	v_cvt_pk_bf16_f32 v43, v59, v61
	global_store_dwordx4 v[44:45], v[40:43], off
	s_waitcnt lgkmcnt(0)

.LBB0_46:
	s_andn2_b64 vcc, exec, s[0:1]
	s_cbranch_vccnz .LBB0_112
	s_and_b32 s68, s4, 0x3c0
	s_add_i32 s0, s12, 0xc00
	s_and_b32 s43, s0, 0x1ffe0
	s_lshl_b32 s34, s43, 2
	v_lshl_add_u64 v[40:41], v[12:13], 0, s[34:35]
	v_add_u32_e32 v232, s68, v65
	s_mov_b32 s98, 0x1000
	v_ashrrev_i32_e32 v233, 31, v232
	v_lshl_add_u64 v[238:239], v[232:233], 2, s[8:9]
	v_and_b32_e32 v237, 31, v64
	v_mul_u32_u24_e32 v236, 33, v65
	v_add_lshl_u32 v236, v236, v237, 2
	s_lshl_b32 s99, s33, 14
	v_add_u32_e32 v236, s99, v236
	v_mad_i64_i32 v[234:235], s[100:101], v232, s98, v[40:41]
	global_load_dword v200, v[234:235], off
	v_add_u32_e32 v232, 2, v232
	v_mad_i64_i32 v[234:235], s[100:101], v232, s98, v[40:41]
	global_load_dword v201, v[234:235], off
	v_add_u32_e32 v232, 2, v232
	v_mad_i64_i32 v[234:235], s[100:101], v232, s98, v[40:41]
	global_load_dword v202, v[234:235], off
	v_add_u32_e32 v232, 2, v232
	v_mad_i64_i32 v[234:235], s[100:101], v232, s98, v[40:41]
	global_load_dword v203, v[234:235], off
	v_add_u32_e32 v232, 2, v232
	v_mad_i64_i32 v[234:235], s[100:101], v232, s98, v[40:41]
	global_load_dword v204, v[234:235], off
	v_add_u32_e32 v232, 2, v232
	v_mad_i64_i32 v[234:235], s[100:101], v232, s98, v[40:41]
	global_load_dword v205, v[234:235], off
	v_add_u32_e32 v232, 2, v232
	v_mad_i64_i32 v[234:235], s[100:101], v232, s98, v[40:41]
	global_load_dword v206, v[234:235], off
	v_add_u32_e32 v232, 2, v232
	v_mad_i64_i32 v[234:235], s[100:101], v232, s98, v[40:41]
	global_load_dword v207, v[234:235], off
	v_add_u32_e32 v232, 2, v232
	v_mad_i64_i32 v[234:235], s[100:101], v232, s98, v[40:41]
	global_load_dword v208, v[234:235], off
	v_add_u32_e32 v232, 2, v232
	v_mad_i64_i32 v[234:235], s[100:101], v232, s98, v[40:41]
	global_load_dword v209, v[234:235], off
	v_add_u32_e32 v232, 2, v232
	v_mad_i64_i32 v[234:235], s[100:101], v232, s98, v[40:41]
	global_load_dword v210, v[234:235], off
	v_add_u32_e32 v232, 2, v232
	v_mad_i64_i32 v[234:235], s[100:101], v232, s98, v[40:41]
	global_load_dword v211, v[234:235], off
	v_add_u32_e32 v232, 2, v232
	v_mad_i64_i32 v[234:235], s[100:101], v232, s98, v[40:41]
	global_load_dword v212, v[234:235], off
	v_add_u32_e32 v232, 2, v232
	v_mad_i64_i32 v[234:235], s[100:101], v232, s98, v[40:41]
	global_load_dword v213, v[234:235], off
	v_add_u32_e32 v232, 2, v232
	v_mad_i64_i32 v[234:235], s[100:101], v232, s98, v[40:41]
	global_load_dword v214, v[234:235], off
	v_add_u32_e32 v232, 2, v232
	v_mad_i64_i32 v[234:235], s[100:101], v232, s98, v[40:41]
	global_load_dword v215, v[234:235], off
	v_add_u32_e32 v232, 2, v232
	global_load_dword v216, v[238:239], off offset:0
	global_load_dword v217, v[238:239], off offset:8
	global_load_dword v218, v[238:239], off offset:16
	global_load_dword v219, v[238:239], off offset:24
	global_load_dword v220, v[238:239], off offset:32
	global_load_dword v221, v[238:239], off offset:40
	global_load_dword v222, v[238:239], off offset:48
	global_load_dword v223, v[238:239], off offset:56
	global_load_dword v224, v[238:239], off offset:64
	global_load_dword v225, v[238:239], off offset:72
	global_load_dword v226, v[238:239], off offset:80
	global_load_dword v227, v[238:239], off offset:88
	global_load_dword v228, v[238:239], off offset:96
	global_load_dword v229, v[238:239], off offset:104
	global_load_dword v230, v[238:239], off offset:112
	global_load_dword v231, v[238:239], off offset:120
	s_waitcnt vmcnt(0)
	v_mul_f32_e32 v200, v200, v216
	v_mul_f32_e32 v201, v201, v217
	v_mul_f32_e32 v202, v202, v218
	v_mul_f32_e32 v203, v203, v219
	v_mul_f32_e32 v204, v204, v220
	v_mul_f32_e32 v205, v205, v221
	v_mul_f32_e32 v206, v206, v222
	v_mul_f32_e32 v207, v207, v223
	v_mul_f32_e32 v208, v208, v224
	v_mul_f32_e32 v209, v209, v225
	v_mul_f32_e32 v210, v210, v226
	v_mul_f32_e32 v211, v211, v227
	v_mul_f32_e32 v212, v212, v228
	v_mul_f32_e32 v213, v213, v229
	v_mul_f32_e32 v214, v214, v230
	v_mul_f32_e32 v215, v215, v231
	ds_write_b32 v236, v200 offset:0
	ds_write_b32 v236, v201 offset:264
	ds_write_b32 v236, v202 offset:528
	ds_write_b32 v236, v203 offset:792
	ds_write_b32 v236, v204 offset:1056
	ds_write_b32 v236, v205 offset:1320
	ds_write_b32 v236, v206 offset:1584
	ds_write_b32 v236, v207 offset:1848
	ds_write_b32 v236, v208 offset:2112
	ds_write_b32 v236, v209 offset:2376
	ds_write_b32 v236, v210 offset:2640
	ds_write_b32 v236, v211 offset:2904
	ds_write_b32 v236, v212 offset:3168
	ds_write_b32 v236, v213 offset:3432
	ds_write_b32 v236, v214 offset:3696
	ds_write_b32 v236, v215 offset:3960
	v_mad_i64_i32 v[234:235], s[100:101], v232, s98, v[40:41]
	global_load_dword v200, v[234:235], off
	v_add_u32_e32 v232, 2, v232
	v_mad_i64_i32 v[234:235], s[100:101], v232, s98, v[40:41]
	global_load_dword v201, v[234:235], off
	v_add_u32_e32 v232, 2, v232
	v_mad_i64_i32 v[234:235], s[100:101], v232, s98, v[40:41]
	global_load_dword v202, v[234:235], off
	v_add_u32_e32 v232, 2, v232
	v_mad_i64_i32 v[234:235], s[100:101], v232, s98, v[40:41]
	global_load_dword v203, v[234:235], off
	v_add_u32_e32 v232, 2, v232
	v_mad_i64_i32 v[234:235], s[100:101], v232, s98, v[40:41]
	global_load_dword v204, v[234:235], off
	v_add_u32_e32 v232, 2, v232
	v_mad_i64_i32 v[234:235], s[100:101], v232, s98, v[40:41]
	global_load_dword v205, v[234:235], off
	v_add_u32_e32 v232, 2, v232
	v_mad_i64_i32 v[234:235], s[100:101], v232, s98, v[40:41]
	global_load_dword v206, v[234:235], off
	v_add_u32_e32 v232, 2, v232
	v_mad_i64_i32 v[234:235], s[100:101], v232, s98, v[40:41]
	global_load_dword v207, v[234:235], off
	v_add_u32_e32 v232, 2, v232
	v_mad_i64_i32 v[234:235], s[100:101], v232, s98, v[40:41]
	global_load_dword v208, v[234:235], off
	v_add_u32_e32 v232, 2, v232
	v_mad_i64_i32 v[234:235], s[100:101], v232, s98, v[40:41]
	global_load_dword v209, v[234:235], off
	v_add_u32_e32 v232, 2, v232
	v_mad_i64_i32 v[234:235], s[100:101], v232, s98, v[40:41]
	global_load_dword v210, v[234:235], off
	v_add_u32_e32 v232, 2, v232
	v_mad_i64_i32 v[234:235], s[100:101], v232, s98, v[40:41]
	global_load_dword v211, v[234:235], off
	v_add_u32_e32 v232, 2, v232
	v_mad_i64_i32 v[234:235], s[100:101], v232, s98, v[40:41]
	global_load_dword v212, v[234:235], off
	v_add_u32_e32 v232, 2, v232
	v_mad_i64_i32 v[234:235], s[100:101], v232, s98, v[40:41]
	global_load_dword v213, v[234:235], off
	v_add_u32_e32 v232, 2, v232
	v_mad_i64_i32 v[234:235], s[100:101], v232, s98, v[40:41]
	global_load_dword v214, v[234:235], off
	v_add_u32_e32 v232, 2, v232
	v_mad_i64_i32 v[234:235], s[100:101], v232, s98, v[40:41]
	global_load_dword v215, v[234:235], off
	v_add_u32_e32 v232, 2, v232
	global_load_dword v216, v[238:239], off offset:128
	global_load_dword v217, v[238:239], off offset:136
	global_load_dword v218, v[238:239], off offset:144
	global_load_dword v219, v[238:239], off offset:152
	global_load_dword v220, v[238:239], off offset:160
	global_load_dword v221, v[238:239], off offset:168
	global_load_dword v222, v[238:239], off offset:176
	global_load_dword v223, v[238:239], off offset:184
	global_load_dword v224, v[238:239], off offset:192
	global_load_dword v225, v[238:239], off offset:200
	global_load_dword v226, v[238:239], off offset:208
	global_load_dword v227, v[238:239], off offset:216
	global_load_dword v228, v[238:239], off offset:224
	global_load_dword v229, v[238:239], off offset:232
	global_load_dword v230, v[238:239], off offset:240
	global_load_dword v231, v[238:239], off offset:248
	s_waitcnt vmcnt(0)
	v_mul_f32_e32 v200, v200, v216
	v_mul_f32_e32 v201, v201, v217
	v_mul_f32_e32 v202, v202, v218
	v_mul_f32_e32 v203, v203, v219
	v_mul_f32_e32 v204, v204, v220
	v_mul_f32_e32 v205, v205, v221
	v_mul_f32_e32 v206, v206, v222
	v_mul_f32_e32 v207, v207, v223
	v_mul_f32_e32 v208, v208, v224
	v_mul_f32_e32 v209, v209, v225
	v_mul_f32_e32 v210, v210, v226
	v_mul_f32_e32 v211, v211, v227
	v_mul_f32_e32 v212, v212, v228
	v_mul_f32_e32 v213, v213, v229
	v_mul_f32_e32 v214, v214, v230
	v_mul_f32_e32 v215, v215, v231
	ds_write_b32 v236, v200 offset:4224
	ds_write_b32 v236, v201 offset:4488
	ds_write_b32 v236, v202 offset:4752
	ds_write_b32 v236, v203 offset:5016
	ds_write_b32 v236, v204 offset:5280
	ds_write_b32 v236, v205 offset:5544
	ds_write_b32 v236, v206 offset:5808
	ds_write_b32 v236, v207 offset:6072
	ds_write_b32 v236, v208 offset:6336
	ds_write_b32 v236, v209 offset:6600
	ds_write_b32 v236, v210 offset:6864
	ds_write_b32 v236, v211 offset:7128
	ds_write_b32 v236, v212 offset:7392
	ds_write_b32 v236, v213 offset:7656
	ds_write_b32 v236, v214 offset:7920
	ds_write_b32 v236, v215 offset:8184
	s_waitcnt lgkmcnt(0)
	ds_read2_b32 v[44:45], v160 offset0:33 offset1:41
	ds_read2_b32 v[46:47], v160 offset1:8
	ds_read2_b32 v[48:49], v160 offset0:66 offset1:74
	ds_read2_b32 v[50:51], v160 offset0:99 offset1:107
	ds_read2_b32 v[52:53], v160 offset0:132 offset1:140
	ds_read2_b32 v[54:55], v160 offset0:165 offset1:173
	ds_read2_b32 v[56:57], v160 offset0:198 offset1:206
	ds_read2_b32 v[58:59], v160 offset0:231 offset1:239
	v_add_u32_e32 v62, s43, v159
	s_lshl_b32 s34, s68, 1
	v_ashrrev_i32_e32 v63, 31, v62
	v_lshl_add_u64 v[60:61], v[32:33], 0, s[34:35]
	v_lshlrev_b64 v[62:63], 11, v[62:63]
	s_waitcnt lgkmcnt(6)
	v_cvt_pk_bf16_f32 v40, v46, v44
	v_lshl_add_u64 v[62:63], v[60:61], 0, v[62:63]
	v_add_u32_e32 v44, s43, v175
	s_waitcnt lgkmcnt(4)
	v_cvt_pk_bf16_f32 v41, v48, v50
	s_waitcnt lgkmcnt(2)
	v_cvt_pk_bf16_f32 v42, v52, v54
	s_waitcnt lgkmcnt(0)
	v_cvt_pk_bf16_f32 v43, v56, v58
	global_store_dwordx4 v[62:63], v[40:43], off
	s_nop 1
	v_cvt_pk_bf16_f32 v40, v47, v45
	v_ashrrev_i32_e32 v45, 31, v44
	v_lshlrev_b64 v[44:45], 11, v[44:45]
	v_cvt_pk_bf16_f32 v41, v49, v51
	v_cvt_pk_bf16_f32 v42, v53, v55
	v_cvt_pk_bf16_f32 v43, v57, v59
	v_lshl_add_u64 v[44:45], v[60:61], 0, v[44:45]
	ds_read2_b32 v[46:47], v160 offset0:16 offset1:24
	ds_read2_b32 v[48:49], v160 offset0:49 offset1:57
	ds_read2_b32 v[50:51], v160 offset0:82 offset1:90
	ds_read2_b32 v[52:53], v160 offset0:115 offset1:123
	ds_read2_b32 v[54:55], v160 offset0:148 offset1:156
	ds_read2_b32 v[56:57], v160 offset0:181 offset1:189
	ds_read2_b32 v[58:59], v160 offset0:214 offset1:222
	ds_read2_b32 v[62:63], v160 offset0:247 offset1:255
	global_store_dwordx4 v[44:45], v[40:43], off
	v_add_u32_e32 v44, s43, v176
	v_ashrrev_i32_e32 v45, 31, v44
	v_lshlrev_b64 v[44:45], 11, v[44:45]
	v_lshl_add_u64 v[44:45], v[60:61], 0, v[44:45]
	s_waitcnt lgkmcnt(6)
	v_cvt_pk_bf16_f32 v40, v46, v48
	s_waitcnt lgkmcnt(4)
	v_cvt_pk_bf16_f32 v41, v50, v52
	s_waitcnt lgkmcnt(2)
	v_cvt_pk_bf16_f32 v42, v54, v56
	s_waitcnt lgkmcnt(0)
	v_cvt_pk_bf16_f32 v43, v58, v62
	global_store_dwordx4 v[44:45], v[40:43], off
	v_add_u32_e32 v44, s43, v177
	v_ashrrev_i32_e32 v45, 31, v44
	v_lshlrev_b64 v[44:45], 11, v[44:45]
	v_lshl_add_u64 v[44:45], v[60:61], 0, v[44:45]
	v_cvt_pk_bf16_f32 v40, v47, v49
	v_cvt_pk_bf16_f32 v41, v51, v53
	v_cvt_pk_bf16_f32 v42, v55, v57
	v_cvt_pk_bf16_f32 v43, v59, v63
	global_store_dwordx4 v[44:45], v[40:43], off
	s_waitcnt lgkmcnt(0)

.LBB0_113:
	s_andn2_b64 vcc, exec, s[0:1]
	s_cbranch_vccnz .LBB0_115
	s_and_b32 s1, s4, 0x3c0
	s_add_i32 s0, s12, 0x1000
	s_and_b32 s0, s0, 0x1ffe0
	s_lshl_b32 s34, s0, 2
	v_lshl_add_u64 v[40:41], v[14:15], 0, s[34:35]
	v_add_u32_e32 v62, s0, v159
	s_lshl_b32 s34, s1, 1
	v_ashrrev_i32_e32 v63, 31, v62
	v_lshlrev_b64 v[62:63], 11, v[62:63]
	v_add_u32_e32 v232, s1, v65
	s_mov_b32 s98, 0x1000
	v_and_b32_e32 v237, 31, v64
	v_mul_u32_u24_e32 v236, 33, v65
	v_add_lshl_u32 v236, v236, v237, 2
	s_lshl_b32 s99, s33, 14
	v_add_u32_e32 v236, s99, v236
	v_mad_i64_i32 v[234:235], s[100:101], v232, s98, v[40:41]
	global_load_dword v200, v[234:235], off
	v_add_u32_e32 v232, 2, v232
	v_mad_i64_i32 v[234:235], s[100:101], v232, s98, v[40:41]
	global_load_dword v201, v[234:235], off
	v_add_u32_e32 v232, 2, v232
	v_mad_i64_i32 v[234:235], s[100:101], v232, s98, v[40:41]
	global_load_dword v202, v[234:235], off
	v_add_u32_e32 v232, 2, v232
	v_mad_i64_i32 v[234:235], s[100:101], v232, s98, v[40:41]
	global_load_dword v203, v[234:235], off
	v_add_u32_e32 v232, 2, v232
	v_mad_i64_i32 v[234:235], s[100:101], v232, s98, v[40:41]
	global_load_dword v204, v[234:235], off
	v_add_u32_e32 v232, 2, v232
	v_mad_i64_i32 v[234:235], s[100:101], v232, s98, v[40:41]
	global_load_dword v205, v[234:235], off
	v_add_u32_e32 v232, 2, v232
	v_mad_i64_i32 v[234:235], s[100:101], v232, s98, v[40:41]
	global_load_dword v206, v[234:235], off
	v_add_u32_e32 v232, 2, v232
	v_mad_i64_i32 v[234:235], s[100:101], v232, s98, v[40:41]
	global_load_dword v207, v[234:235], off
	v_add_u32_e32 v232, 2, v232
	v_mad_i64_i32 v[234:235], s[100:101], v232, s98, v[40:41]
	global_load_dword v208, v[234:235], off
	v_add_u32_e32 v232, 2, v232
	v_mad_i64_i32 v[234:235], s[100:101], v232, s98, v[40:41]
	global_load_dword v209, v[234:235], off
	v_add_u32_e32 v232, 2, v232
	v_mad_i64_i32 v[234:235], s[100:101], v232, s98, v[40:41]
	global_load_dword v210, v[234:235], off
	v_add_u32_e32 v232, 2, v232
	v_mad_i64_i32 v[234:235], s[100:101], v232, s98, v[40:41]
	global_load_dword v211, v[234:235], off
	v_add_u32_e32 v232, 2, v232
	v_mad_i64_i32 v[234:235], s[100:101], v232, s98, v[40:41]
	global_load_dword v212, v[234:235], off
	v_add_u32_e32 v232, 2, v232
	v_mad_i64_i32 v[234:235], s[100:101], v232, s98, v[40:41]
	global_load_dword v213, v[234:235], off
	v_add_u32_e32 v232, 2, v232
	v_mad_i64_i32 v[234:235], s[100:101], v232, s98, v[40:41]
	global_load_dword v214, v[234:235], off
	v_add_u32_e32 v232, 2, v232
	v_mad_i64_i32 v[234:235], s[100:101], v232, s98, v[40:41]
	global_load_dword v215, v[234:235], off
	v_add_u32_e32 v232, 2, v232
	v_mad_i64_i32 v[234:235], s[100:101], v232, s98, v[40:41]
	global_load_dword v216, v[234:235], off
	v_add_u32_e32 v232, 2, v232
	v_mad_i64_i32 v[234:235], s[100:101], v232, s98, v[40:41]
	global_load_dword v217, v[234:235], off
	v_add_u32_e32 v232, 2, v232
	v_mad_i64_i32 v[234:235], s[100:101], v232, s98, v[40:41]
	global_load_dword v218, v[234:235], off
	v_add_u32_e32 v232, 2, v232
	v_mad_i64_i32 v[234:235], s[100:101], v232, s98, v[40:41]
	global_load_dword v219, v[234:235], off
	v_add_u32_e32 v232, 2, v232
	v_mad_i64_i32 v[234:235], s[100:101], v232, s98, v[40:41]
	global_load_dword v220, v[234:235], off
	v_add_u32_e32 v232, 2, v232
	v_mad_i64_i32 v[234:235], s[100:101], v232, s98, v[40:41]
	global_load_dword v221, v[234:235], off
	v_add_u32_e32 v232, 2, v232
	v_mad_i64_i32 v[234:235], s[100:101], v232, s98, v[40:41]
	global_load_dword v222, v[234:235], off
	v_add_u32_e32 v232, 2, v232
	v_mad_i64_i32 v[234:235], s[100:101], v232, s98, v[40:41]
	global_load_dword v223, v[234:235], off
	v_add_u32_e32 v232, 2, v232
	v_mad_i64_i32 v[234:235], s[100:101], v232, s98, v[40:41]
	global_load_dword v224, v[234:235], off
	v_add_u32_e32 v232, 2, v232
	v_mad_i64_i32 v[234:235], s[100:101], v232, s98, v[40:41]
	global_load_dword v225, v[234:235], off
	v_add_u32_e32 v232, 2, v232
	v_mad_i64_i32 v[234:235], s[100:101], v232, s98, v[40:41]
	global_load_dword v226, v[234:235], off
	v_add_u32_e32 v232, 2, v232
	v_mad_i64_i32 v[234:235], s[100:101], v232, s98, v[40:41]
	global_load_dword v227, v[234:235], off
	v_add_u32_e32 v232, 2, v232
	v_mad_i64_i32 v[234:235], s[100:101], v232, s98, v[40:41]
	global_load_dword v228, v[234:235], off
	v_add_u32_e32 v232, 2, v232
	v_mad_i64_i32 v[234:235], s[100:101], v232, s98, v[40:41]
	global_load_dword v229, v[234:235], off
	v_add_u32_e32 v232, 2, v232
	v_mad_i64_i32 v[234:235], s[100:101], v232, s98, v[40:41]
	global_load_dword v230, v[234:235], off
	v_add_u32_e32 v232, 2, v232
	v_mad_i64_i32 v[234:235], s[100:101], v232, s98, v[40:41]
	global_load_dword v231, v[234:235], off
	s_waitcnt vmcnt(0)
	ds_write_b32 v236, v200 offset:0
	ds_write_b32 v236, v201 offset:264
	ds_write_b32 v236, v202 offset:528
	ds_write_b32 v236, v203 offset:792
	ds_write_b32 v236, v204 offset:1056
	ds_write_b32 v236, v205 offset:1320
	ds_write_b32 v236, v206 offset:1584
	ds_write_b32 v236, v207 offset:1848
	ds_write_b32 v236, v208 offset:2112
	ds_write_b32 v236, v209 offset:2376
	ds_write_b32 v236, v210 offset:2640
	ds_write_b32 v236, v211 offset:2904
	ds_write_b32 v236, v212 offset:3168
	ds_write_b32 v236, v213 offset:3432
	ds_write_b32 v236, v214 offset:3696
	ds_write_b32 v236, v215 offset:3960
	ds_write_b32 v236, v216 offset:4224
	ds_write_b32 v236, v217 offset:4488
	ds_write_b32 v236, v218 offset:4752
	ds_write_b32 v236, v219 offset:5016
	ds_write_b32 v236, v220 offset:5280
	ds_write_b32 v236, v221 offset:5544
	ds_write_b32 v236, v222 offset:5808
	ds_write_b32 v236, v223 offset:6072
	ds_write_b32 v236, v224 offset:6336
	ds_write_b32 v236, v225 offset:6600
	ds_write_b32 v236, v226 offset:6864
	ds_write_b32 v236, v227 offset:7128
	ds_write_b32 v236, v228 offset:7392
	ds_write_b32 v236, v229 offset:7656
	ds_write_b32 v236, v230 offset:7920
	ds_write_b32 v236, v231 offset:8184
	s_waitcnt lgkmcnt(0)
	ds_read2_b32 v[46:47], v160 offset0:33 offset1:41
	ds_read2_b32 v[48:49], v160 offset1:8
	ds_read2_b32 v[50:51], v160 offset0:66 offset1:74
	ds_read2_b32 v[52:53], v160 offset0:99 offset1:107
	ds_read2_b32 v[54:55], v160 offset0:132 offset1:140
	ds_read2_b32 v[56:57], v160 offset0:165 offset1:173
	ds_read2_b32 v[58:59], v160 offset0:198 offset1:206
	ds_read2_b32 v[60:61], v160 offset0:231 offset1:239
	v_lshl_add_u64 v[44:45], v[34:35], 0, s[34:35]
	s_waitcnt lgkmcnt(6)
	v_cvt_pk_bf16_f32 v40, v48, v46
	v_lshl_add_u64 v[62:63], v[44:45], 0, v[62:63]
	v_add_u32_e32 v46, s0, v175
	s_waitcnt lgkmcnt(4)
	v_cvt_pk_bf16_f32 v41, v50, v52
	s_waitcnt lgkmcnt(2)
	v_cvt_pk_bf16_f32 v42, v54, v56
	s_waitcnt lgkmcnt(0)
	v_cvt_pk_bf16_f32 v43, v58, v60
	global_store_dwordx4 v[62:63], v[40:43], off
	v_add_u32_e32 v62, s0, v176
	v_ashrrev_i32_e32 v63, 31, v62
	v_cvt_pk_bf16_f32 v40, v49, v47
	v_ashrrev_i32_e32 v47, 31, v46
	v_lshlrev_b64 v[46:47], 11, v[46:47]
	v_lshl_add_u64 v[46:47], v[44:45], 0, v[46:47]
	v_cvt_pk_bf16_f32 v41, v51, v53
	v_cvt_pk_bf16_f32 v42, v55, v57
	v_cvt_pk_bf16_f32 v43, v59, v61
	global_store_dwordx4 v[46:47], v[40:43], off
	ds_read2_b32 v[46:47], v160 offset0:16 offset1:24
	ds_read2_b32 v[48:49], v160 offset0:49 offset1:57
	ds_read2_b32 v[50:51], v160 offset0:82 offset1:90
	ds_read2_b32 v[52:53], v160 offset0:115 offset1:123
	ds_read2_b32 v[54:55], v160 offset0:148 offset1:156
	ds_read2_b32 v[56:57], v160 offset0:181 offset1:189
	ds_read2_b32 v[58:59], v160 offset0:214 offset1:222
	ds_read2_b32 v[60:61], v160 offset0:247 offset1:255
	v_lshlrev_b64 v[62:63], 11, v[62:63]
	s_waitcnt lgkmcnt(6)
	v_cvt_pk_bf16_f32 v40, v46, v48
	v_lshl_add_u64 v[62:63], v[44:45], 0, v[62:63]
	v_add_u32_e32 v46, s0, v177
	s_waitcnt lgkmcnt(4)
	v_cvt_pk_bf16_f32 v41, v50, v52
	s_waitcnt lgkmcnt(2)
	v_cvt_pk_bf16_f32 v42, v54, v56
	s_waitcnt lgkmcnt(0)
	v_cvt_pk_bf16_f32 v43, v58, v60
	global_store_dwordx4 v[62:63], v[40:43], off
	s_nop 1
	v_cvt_pk_bf16_f32 v40, v47, v49
	v_ashrrev_i32_e32 v47, 31, v46
	v_lshlrev_b64 v[46:47], 11, v[46:47]
	v_lshl_add_u64 v[44:45], v[44:45], 0, v[46:47]
	v_cvt_pk_bf16_f32 v41, v51, v53
	v_cvt_pk_bf16_f32 v42, v55, v57
	v_cvt_pk_bf16_f32 v43, v59, v61
	global_store_dwordx4 v[44:45], v[40:43], off
	s_waitcnt lgkmcnt(0)

.LBB0_116:
	s_andn2_b64 vcc, exec, s[0:1]
	s_cbranch_vccnz .LBB0_118
	s_add_i32 s0, s42, 0xeb80
	s_and_b32 s1, s0, 0xffff
	s_mul_i32 s1, s1, 0xba2f
	s_lshr_b32 s34, s1, 16
	s_lshr_b32 s1, s1, 21
	s_mul_i32 s1, s1, 44
	s_sub_i32 s0, s0, s1
	s_lshl_b32 s0, s0, 6
	s_and_b32 s1, s0, 0xffc0
	s_and_b32 s0, s34, 0xffe0
	s_lshl_b32 s34, s0, 2
	v_lshl_add_u64 v[40:41], v[16:17], 0, s[34:35]
	s_lshl_b32 s34, s1, 1
	v_add_u32_e32 v232, s1, v65
	s_mov_b32 s98, 0x1000
	v_and_b32_e32 v237, 31, v64
	v_mul_u32_u24_e32 v236, 33, v65
	v_add_lshl_u32 v236, v236, v237, 2
	s_lshl_b32 s99, s33, 14
	v_add_u32_e32 v236, s99, v236
	v_mad_i64_i32 v[234:235], s[100:101], v232, s98, v[40:41]
	global_load_dword v200, v[234:235], off
	v_add_u32_e32 v232, 2, v232
	v_mad_i64_i32 v[234:235], s[100:101], v232, s98, v[40:41]
	global_load_dword v201, v[234:235], off
	v_add_u32_e32 v232, 2, v232
	v_mad_i64_i32 v[234:235], s[100:101], v232, s98, v[40:41]
	global_load_dword v202, v[234:235], off
	v_add_u32_e32 v232, 2, v232
	v_mad_i64_i32 v[234:235], s[100:101], v232, s98, v[40:41]
	global_load_dword v203, v[234:235], off
	v_add_u32_e32 v232, 2, v232
	v_mad_i64_i32 v[234:235], s[100:101], v232, s98, v[40:41]
	global_load_dword v204, v[234:235], off
	v_add_u32_e32 v232, 2, v232
	v_mad_i64_i32 v[234:235], s[100:101], v232, s98, v[40:41]
	global_load_dword v205, v[234:235], off
	v_add_u32_e32 v232, 2, v232
	v_mad_i64_i32 v[234:235], s[100:101], v232, s98, v[40:41]
	global_load_dword v206, v[234:235], off
	v_add_u32_e32 v232, 2, v232
	v_mad_i64_i32 v[234:235], s[100:101], v232, s98, v[40:41]
	global_load_dword v207, v[234:235], off
	v_add_u32_e32 v232, 2, v232
	v_mad_i64_i32 v[234:235], s[100:101], v232, s98, v[40:41]
	global_load_dword v208, v[234:235], off
	v_add_u32_e32 v232, 2, v232
	v_mad_i64_i32 v[234:235], s[100:101], v232, s98, v[40:41]
	global_load_dword v209, v[234:235], off
	v_add_u32_e32 v232, 2, v232
	v_mad_i64_i32 v[234:235], s[100:101], v232, s98, v[40:41]
	global_load_dword v210, v[234:235], off
	v_add_u32_e32 v232, 2, v232
	v_mad_i64_i32 v[234:235], s[100:101], v232, s98, v[40:41]
	global_load_dword v211, v[234:235], off
	v_add_u32_e32 v232, 2, v232
	v_mad_i64_i32 v[234:235], s[100:101], v232, s98, v[40:41]
	global_load_dword v212, v[234:235], off
	v_add_u32_e32 v232, 2, v232
	v_mad_i64_i32 v[234:235], s[100:101], v232, s98, v[40:41]
	global_load_dword v213, v[234:235], off
	v_add_u32_e32 v232, 2, v232
	v_mad_i64_i32 v[234:235], s[100:101], v232, s98, v[40:41]
	global_load_dword v214, v[234:235], off
	v_add_u32_e32 v232, 2, v232
	v_mad_i64_i32 v[234:235], s[100:101], v232, s98, v[40:41]
	global_load_dword v215, v[234:235], off
	v_add_u32_e32 v232, 2, v232
	v_mad_i64_i32 v[234:235], s[100:101], v232, s98, v[40:41]
	global_load_dword v216, v[234:235], off
	v_add_u32_e32 v232, 2, v232
	v_mad_i64_i32 v[234:235], s[100:101], v232, s98, v[40:41]
	global_load_dword v217, v[234:235], off
	v_add_u32_e32 v232, 2, v232
	v_mad_i64_i32 v[234:235], s[100:101], v232, s98, v[40:41]
	global_load_dword v218, v[234:235], off
	v_add_u32_e32 v232, 2, v232
	v_mad_i64_i32 v[234:235], s[100:101], v232, s98, v[40:41]
	global_load_dword v219, v[234:235], off
	v_add_u32_e32 v232, 2, v232
	v_mad_i64_i32 v[234:235], s[100:101], v232, s98, v[40:41]
	global_load_dword v220, v[234:235], off
	v_add_u32_e32 v232, 2, v232
	v_mad_i64_i32 v[234:235], s[100:101], v232, s98, v[40:41]
	global_load_dword v221, v[234:235], off
	v_add_u32_e32 v232, 2, v232
	v_mad_i64_i32 v[234:235], s[100:101], v232, s98, v[40:41]
	global_load_dword v222, v[234:235], off
	v_add_u32_e32 v232, 2, v232
	v_mad_i64_i32 v[234:235], s[100:101], v232, s98, v[40:41]
	global_load_dword v223, v[234:235], off
	v_add_u32_e32 v232, 2, v232
	v_mad_i64_i32 v[234:235], s[100:101], v232, s98, v[40:41]
	global_load_dword v224, v[234:235], off
	v_add_u32_e32 v232, 2, v232
	v_mad_i64_i32 v[234:235], s[100:101], v232, s98, v[40:41]
	global_load_dword v225, v[234:235], off
	v_add_u32_e32 v232, 2, v232
	v_mad_i64_i32 v[234:235], s[100:101], v232, s98, v[40:41]
	global_load_dword v226, v[234:235], off
	v_add_u32_e32 v232, 2, v232
	v_mad_i64_i32 v[234:235], s[100:101], v232, s98, v[40:41]
	global_load_dword v227, v[234:235], off
	v_add_u32_e32 v232, 2, v232
	v_mad_i64_i32 v[234:235], s[100:101], v232, s98, v[40:41]
	global_load_dword v228, v[234:235], off
	v_add_u32_e32 v232, 2, v232
	v_mad_i64_i32 v[234:235], s[100:101], v232, s98, v[40:41]
	global_load_dword v229, v[234:235], off
	v_add_u32_e32 v232, 2, v232
	v_mad_i64_i32 v[234:235], s[100:101], v232, s98, v[40:41]
	global_load_dword v230, v[234:235], off
	v_add_u32_e32 v232, 2, v232
	v_mad_i64_i32 v[234:235], s[100:101], v232, s98, v[40:41]
	global_load_dword v231, v[234:235], off
	s_waitcnt vmcnt(0)
	ds_write_b32 v236, v200 offset:0
	ds_write_b32 v236, v201 offset:264
	ds_write_b32 v236, v202 offset:528
	ds_write_b32 v236, v203 offset:792
	ds_write_b32 v236, v204 offset:1056
	ds_write_b32 v236, v205 offset:1320
	ds_write_b32 v236, v206 offset:1584
	ds_write_b32 v236, v207 offset:1848
	ds_write_b32 v236, v208 offset:2112
	ds_write_b32 v236, v209 offset:2376
	ds_write_b32 v236, v210 offset:2640
	ds_write_b32 v236, v211 offset:2904
	ds_write_b32 v236, v212 offset:3168
	ds_write_b32 v236, v213 offset:3432
	ds_write_b32 v236, v214 offset:3696
	ds_write_b32 v236, v215 offset:3960
	ds_write_b32 v236, v216 offset:4224
	ds_write_b32 v236, v217 offset:4488
	ds_write_b32 v236, v218 offset:4752
	ds_write_b32 v236, v219 offset:5016
	ds_write_b32 v236, v220 offset:5280
	ds_write_b32 v236, v221 offset:5544
	ds_write_b32 v236, v222 offset:5808
	ds_write_b32 v236, v223 offset:6072
	ds_write_b32 v236, v224 offset:6336
	ds_write_b32 v236, v225 offset:6600
	ds_write_b32 v236, v226 offset:6864
	ds_write_b32 v236, v227 offset:7128
	ds_write_b32 v236, v228 offset:7392
	ds_write_b32 v236, v229 offset:7656
	ds_write_b32 v236, v230 offset:7920
	ds_write_b32 v236, v231 offset:8184
	s_waitcnt lgkmcnt(0)
	ds_read2_b32 v[46:47], v160 offset0:33 offset1:41
	ds_read2_b32 v[48:49], v160 offset1:8
	ds_read2_b32 v[50:51], v160 offset0:66 offset1:74
	ds_read2_b32 v[52:53], v160 offset0:99 offset1:107
	ds_read2_b32 v[54:55], v160 offset0:132 offset1:140
	ds_read2_b32 v[56:57], v160 offset0:165 offset1:173
	ds_read2_b32 v[58:59], v160 offset0:198 offset1:206
	ds_read2_b32 v[60:61], v160 offset0:231 offset1:239
	v_lshl_add_u64 v[44:45], v[36:37], 0, s[34:35]
	s_waitcnt lgkmcnt(6)
	v_cvt_pk_bf16_f32 v40, v48, v46
	v_add_u32_e32 v46, s0, v159
	v_mad_i64_i32 v[62:63], s[52:53], v46, s16, v[44:45]
	v_add_u32_e32 v46, s0, v175
	s_waitcnt lgkmcnt(4)
	v_cvt_pk_bf16_f32 v41, v50, v52
	s_waitcnt lgkmcnt(2)
	v_cvt_pk_bf16_f32 v42, v54, v56
	s_waitcnt lgkmcnt(0)
	v_cvt_pk_bf16_f32 v43, v58, v60
	global_store_dwordx4 v[62:63], v[40:43], off
	s_nop 1
	v_cvt_pk_bf16_f32 v40, v49, v47
	v_mad_i64_i32 v[46:47], s[52:53], v46, s16, v[44:45]
	v_cvt_pk_bf16_f32 v41, v51, v53
	v_cvt_pk_bf16_f32 v42, v55, v57
	v_cvt_pk_bf16_f32 v43, v59, v61
	global_store_dwordx4 v[46:47], v[40:43], off
	ds_read2_b32 v[46:47], v160 offset0:16 offset1:24
	ds_read2_b32 v[48:49], v160 offset0:49 offset1:57
	ds_read2_b32 v[50:51], v160 offset0:82 offset1:90
	ds_read2_b32 v[52:53], v160 offset0:115 offset1:123
	ds_read2_b32 v[54:55], v160 offset0:148 offset1:156
	ds_read2_b32 v[56:57], v160 offset0:181 offset1:189
	ds_read2_b32 v[58:59], v160 offset0:214 offset1:222
	ds_read2_b32 v[60:61], v160 offset0:247 offset1:255
	s_waitcnt lgkmcnt(6)
	v_cvt_pk_bf16_f32 v40, v46, v48
	v_add_u32_e32 v46, s0, v176
	v_mad_i64_i32 v[62:63], s[52:53], v46, s16, v[44:45]
	v_add_u32_e32 v46, s0, v177
	s_waitcnt lgkmcnt(4)
	v_cvt_pk_bf16_f32 v41, v50, v52
	s_waitcnt lgkmcnt(2)
	v_cvt_pk_bf16_f32 v42, v54, v56
	s_waitcnt lgkmcnt(0)
	v_cvt_pk_bf16_f32 v43, v58, v60
	v_mad_i64_i32 v[44:45], s[0:1], v46, s16, v[44:45]
	global_store_dwordx4 v[62:63], v[40:43], off
	s_nop 1
	v_cvt_pk_bf16_f32 v40, v47, v49
	v_cvt_pk_bf16_f32 v41, v51, v53
	v_cvt_pk_bf16_f32 v42, v55, v57
	v_cvt_pk_bf16_f32 v43, v59, v61
	global_store_dwordx4 v[44:45], v[40:43], off
	s_waitcnt lgkmcnt(0)

.LBB0_119:
	s_andn2_b64 vcc, exec, s[0:1]
	s_cbranch_vccnz .LBB0_185
	s_add_i32 s0, s12, 0x2e00
	s_and_b32 s43, s0, 0x1ffe0
	s_and_b32 s68, s4, 0x3c0
	s_lshl_b32 s34, s43, 2
	v_lshl_add_u64 v[40:41], v[18:19], 0, s[34:35]
	v_add_u32_e32 v232, s68, v65
	v_ashrrev_i32_e32 v233, 31, v232
	v_lshl_add_u64 v[238:239], v[232:233], 2, s[40:41]
	v_and_b32_e32 v237, 31, v64
	v_mul_u32_u24_e32 v236, 33, v65
	v_add_lshl_u32 v236, v236, v237, 2
	s_lshl_b32 s99, s33, 14
	v_add_u32_e32 v236, s99, v236
	v_mad_i64_i32 v[234:235], s[100:101], v232, s17, v[40:41]
	global_load_dword v200, v[234:235], off
	v_add_u32_e32 v232, 2, v232
	v_mad_i64_i32 v[234:235], s[100:101], v232, s17, v[40:41]
	global_load_dword v201, v[234:235], off
	v_add_u32_e32 v232, 2, v232
	v_mad_i64_i32 v[234:235], s[100:101], v232, s17, v[40:41]
	global_load_dword v202, v[234:235], off
	v_add_u32_e32 v232, 2, v232
	v_mad_i64_i32 v[234:235], s[100:101], v232, s17, v[40:41]
	global_load_dword v203, v[234:235], off
	v_add_u32_e32 v232, 2, v232
	v_mad_i64_i32 v[234:235], s[100:101], v232, s17, v[40:41]
	global_load_dword v204, v[234:235], off
	v_add_u32_e32 v232, 2, v232
	v_mad_i64_i32 v[234:235], s[100:101], v232, s17, v[40:41]
	global_load_dword v205, v[234:235], off
	v_add_u32_e32 v232, 2, v232
	v_mad_i64_i32 v[234:235], s[100:101], v232, s17, v[40:41]
	global_load_dword v206, v[234:235], off
	v_add_u32_e32 v232, 2, v232
	v_mad_i64_i32 v[234:235], s[100:101], v232, s17, v[40:41]
	global_load_dword v207, v[234:235], off
	v_add_u32_e32 v232, 2, v232
	v_mad_i64_i32 v[234:235], s[100:101], v232, s17, v[40:41]
	global_load_dword v208, v[234:235], off
	v_add_u32_e32 v232, 2, v232
	v_mad_i64_i32 v[234:235], s[100:101], v232, s17, v[40:41]
	global_load_dword v209, v[234:235], off
	v_add_u32_e32 v232, 2, v232
	v_mad_i64_i32 v[234:235], s[100:101], v232, s17, v[40:41]
	global_load_dword v210, v[234:235], off
	v_add_u32_e32 v232, 2, v232
	v_mad_i64_i32 v[234:235], s[100:101], v232, s17, v[40:41]
	global_load_dword v211, v[234:235], off
	v_add_u32_e32 v232, 2, v232
	v_mad_i64_i32 v[234:235], s[100:101], v232, s17, v[40:41]
	global_load_dword v212, v[234:235], off
	v_add_u32_e32 v232, 2, v232
	v_mad_i64_i32 v[234:235], s[100:101], v232, s17, v[40:41]
	global_load_dword v213, v[234:235], off
	v_add_u32_e32 v232, 2, v232
	v_mad_i64_i32 v[234:235], s[100:101], v232, s17, v[40:41]
	global_load_dword v214, v[234:235], off
	v_add_u32_e32 v232, 2, v232
	v_mad_i64_i32 v[234:235], s[100:101], v232, s17, v[40:41]
	global_load_dword v215, v[234:235], off
	v_add_u32_e32 v232, 2, v232
	global_load_dword v216, v[238:239], off offset:0
	global_load_dword v217, v[238:239], off offset:8
	global_load_dword v218, v[238:239], off offset:16
	global_load_dword v219, v[238:239], off offset:24
	global_load_dword v220, v[238:239], off offset:32
	global_load_dword v221, v[238:239], off offset:40
	global_load_dword v222, v[238:239], off offset:48
	global_load_dword v223, v[238:239], off offset:56
	global_load_dword v224, v[238:239], off offset:64
	global_load_dword v225, v[238:239], off offset:72
	global_load_dword v226, v[238:239], off offset:80
	global_load_dword v227, v[238:239], off offset:88
	global_load_dword v228, v[238:239], off offset:96
	global_load_dword v229, v[238:239], off offset:104
	global_load_dword v230, v[238:239], off offset:112
	global_load_dword v231, v[238:239], off offset:120
	s_waitcnt vmcnt(0)
	v_mul_f32_e32 v200, v200, v216
	v_mul_f32_e32 v201, v201, v217
	v_mul_f32_e32 v202, v202, v218
	v_mul_f32_e32 v203, v203, v219
	v_mul_f32_e32 v204, v204, v220
	v_mul_f32_e32 v205, v205, v221
	v_mul_f32_e32 v206, v206, v222
	v_mul_f32_e32 v207, v207, v223
	v_mul_f32_e32 v208, v208, v224
	v_mul_f32_e32 v209, v209, v225
	v_mul_f32_e32 v210, v210, v226
	v_mul_f32_e32 v211, v211, v227
	v_mul_f32_e32 v212, v212, v228
	v_mul_f32_e32 v213, v213, v229
	v_mul_f32_e32 v214, v214, v230
	v_mul_f32_e32 v215, v215, v231
	ds_write_b32 v236, v200 offset:0
	ds_write_b32 v236, v201 offset:264
	ds_write_b32 v236, v202 offset:528
	ds_write_b32 v236, v203 offset:792
	ds_write_b32 v236, v204 offset:1056
	ds_write_b32 v236, v205 offset:1320
	ds_write_b32 v236, v206 offset:1584
	ds_write_b32 v236, v207 offset:1848
	ds_write_b32 v236, v208 offset:2112
	ds_write_b32 v236, v209 offset:2376
	ds_write_b32 v236, v210 offset:2640
	ds_write_b32 v236, v211 offset:2904
	ds_write_b32 v236, v212 offset:3168
	ds_write_b32 v236, v213 offset:3432
	ds_write_b32 v236, v214 offset:3696
	ds_write_b32 v236, v215 offset:3960
	v_mad_i64_i32 v[234:235], s[100:101], v232, s17, v[40:41]
	global_load_dword v200, v[234:235], off
	v_add_u32_e32 v232, 2, v232
	v_mad_i64_i32 v[234:235], s[100:101], v232, s17, v[40:41]
	global_load_dword v201, v[234:235], off
	v_add_u32_e32 v232, 2, v232
	v_mad_i64_i32 v[234:235], s[100:101], v232, s17, v[40:41]
	global_load_dword v202, v[234:235], off
	v_add_u32_e32 v232, 2, v232
	v_mad_i64_i32 v[234:235], s[100:101], v232, s17, v[40:41]
	global_load_dword v203, v[234:235], off
	v_add_u32_e32 v232, 2, v232
	v_mad_i64_i32 v[234:235], s[100:101], v232, s17, v[40:41]
	global_load_dword v204, v[234:235], off
	v_add_u32_e32 v232, 2, v232
	v_mad_i64_i32 v[234:235], s[100:101], v232, s17, v[40:41]
	global_load_dword v205, v[234:235], off
	v_add_u32_e32 v232, 2, v232
	v_mad_i64_i32 v[234:235], s[100:101], v232, s17, v[40:41]
	global_load_dword v206, v[234:235], off
	v_add_u32_e32 v232, 2, v232
	v_mad_i64_i32 v[234:235], s[100:101], v232, s17, v[40:41]
	global_load_dword v207, v[234:235], off
	v_add_u32_e32 v232, 2, v232
	v_mad_i64_i32 v[234:235], s[100:101], v232, s17, v[40:41]
	global_load_dword v208, v[234:235], off
	v_add_u32_e32 v232, 2, v232
	v_mad_i64_i32 v[234:235], s[100:101], v232, s17, v[40:41]
	global_load_dword v209, v[234:235], off
	v_add_u32_e32 v232, 2, v232
	v_mad_i64_i32 v[234:235], s[100:101], v232, s17, v[40:41]
	global_load_dword v210, v[234:235], off
	v_add_u32_e32 v232, 2, v232
	v_mad_i64_i32 v[234:235], s[100:101], v232, s17, v[40:41]
	global_load_dword v211, v[234:235], off
	v_add_u32_e32 v232, 2, v232
	v_mad_i64_i32 v[234:235], s[100:101], v232, s17, v[40:41]
	global_load_dword v212, v[234:235], off
	v_add_u32_e32 v232, 2, v232
	v_mad_i64_i32 v[234:235], s[100:101], v232, s17, v[40:41]
	global_load_dword v213, v[234:235], off
	v_add_u32_e32 v232, 2, v232
	v_mad_i64_i32 v[234:235], s[100:101], v232, s17, v[40:41]
	global_load_dword v214, v[234:235], off
	v_add_u32_e32 v232, 2, v232
	v_mad_i64_i32 v[234:235], s[100:101], v232, s17, v[40:41]
	global_load_dword v215, v[234:235], off
	v_add_u32_e32 v232, 2, v232
	global_load_dword v216, v[238:239], off offset:128
	global_load_dword v217, v[238:239], off offset:136
	global_load_dword v218, v[238:239], off offset:144
	global_load_dword v219, v[238:239], off offset:152
	global_load_dword v220, v[238:239], off offset:160
	global_load_dword v221, v[238:239], off offset:168
	global_load_dword v222, v[238:239], off offset:176
	global_load_dword v223, v[238:239], off offset:184
	global_load_dword v224, v[238:239], off offset:192
	global_load_dword v225, v[238:239], off offset:200
	global_load_dword v226, v[238:239], off offset:208
	global_load_dword v227, v[238:239], off offset:216
	global_load_dword v228, v[238:239], off offset:224
	global_load_dword v229, v[238:239], off offset:232
	global_load_dword v230, v[238:239], off offset:240
	global_load_dword v231, v[238:239], off offset:248
	s_waitcnt vmcnt(0)
	v_mul_f32_e32 v200, v200, v216
	v_mul_f32_e32 v201, v201, v217
	v_mul_f32_e32 v202, v202, v218
	v_mul_f32_e32 v203, v203, v219
	v_mul_f32_e32 v204, v204, v220
	v_mul_f32_e32 v205, v205, v221
	v_mul_f32_e32 v206, v206, v222
	v_mul_f32_e32 v207, v207, v223
	v_mul_f32_e32 v208, v208, v224
	v_mul_f32_e32 v209, v209, v225
	v_mul_f32_e32 v210, v210, v226
	v_mul_f32_e32 v211, v211, v227
	v_mul_f32_e32 v212, v212, v228
	v_mul_f32_e32 v213, v213, v229
	v_mul_f32_e32 v214, v214, v230
	v_mul_f32_e32 v215, v215, v231
	ds_write_b32 v236, v200 offset:4224
	ds_write_b32 v236, v201 offset:4488
	ds_write_b32 v236, v202 offset:4752
	ds_write_b32 v236, v203 offset:5016
	ds_write_b32 v236, v204 offset:5280
	ds_write_b32 v236, v205 offset:5544
	ds_write_b32 v236, v206 offset:5808
	ds_write_b32 v236, v207 offset:6072
	ds_write_b32 v236, v208 offset:6336
	ds_write_b32 v236, v209 offset:6600
	ds_write_b32 v236, v210 offset:6864
	ds_write_b32 v236, v211 offset:7128
	ds_write_b32 v236, v212 offset:7392
	ds_write_b32 v236, v213 offset:7656
	ds_write_b32 v236, v214 offset:7920
	ds_write_b32 v236, v215 offset:8184
	s_waitcnt lgkmcnt(0)
	ds_read2_b32 v[44:45], v160 offset0:33 offset1:41
	ds_read2_b32 v[46:47], v160 offset1:8
	ds_read2_b32 v[48:49], v160 offset0:66 offset1:74
	ds_read2_b32 v[50:51], v160 offset0:99 offset1:107
	ds_read2_b32 v[52:53], v160 offset0:132 offset1:140
	ds_read2_b32 v[54:55], v160 offset0:165 offset1:173
	ds_read2_b32 v[56:57], v160 offset0:198 offset1:206
	ds_read2_b32 v[58:59], v160 offset0:231 offset1:239
	v_add_u32_e32 v62, s43, v159
	s_lshl_b32 s34, s68, 1
	v_ashrrev_i32_e32 v63, 31, v62
	v_lshl_add_u64 v[60:61], v[2:3], 0, s[34:35]
	v_lshlrev_b64 v[62:63], 11, v[62:63]
	s_waitcnt lgkmcnt(6)
	v_cvt_pk_bf16_f32 v40, v46, v44
	v_lshl_add_u64 v[62:63], v[60:61], 0, v[62:63]
	v_add_u32_e32 v44, s43, v175
	s_waitcnt lgkmcnt(4)
	v_cvt_pk_bf16_f32 v41, v48, v50
	s_waitcnt lgkmcnt(2)
	v_cvt_pk_bf16_f32 v42, v52, v54
	s_waitcnt lgkmcnt(0)
	v_cvt_pk_bf16_f32 v43, v56, v58
	global_store_dwordx4 v[62:63], v[40:43], off
	s_nop 1
	v_cvt_pk_bf16_f32 v40, v47, v45
	v_ashrrev_i32_e32 v45, 31, v44
	v_lshlrev_b64 v[44:45], 11, v[44:45]
	v_cvt_pk_bf16_f32 v41, v49, v51
	v_cvt_pk_bf16_f32 v42, v53, v55
	v_cvt_pk_bf16_f32 v43, v57, v59
	v_lshl_add_u64 v[44:45], v[60:61], 0, v[44:45]
	ds_read2_b32 v[46:47], v160 offset0:16 offset1:24
	ds_read2_b32 v[48:49], v160 offset0:49 offset1:57
	ds_read2_b32 v[50:51], v160 offset0:82 offset1:90
	ds_read2_b32 v[52:53], v160 offset0:115 offset1:123
	ds_read2_b32 v[54:55], v160 offset0:148 offset1:156
	ds_read2_b32 v[56:57], v160 offset0:181 offset1:189
	ds_read2_b32 v[58:59], v160 offset0:214 offset1:222
	ds_read2_b32 v[62:63], v160 offset0:247 offset1:255
	global_store_dwordx4 v[44:45], v[40:43], off
	v_add_u32_e32 v44, s43, v176
	v_ashrrev_i32_e32 v45, 31, v44
	v_lshlrev_b64 v[44:45], 11, v[44:45]
	v_lshl_add_u64 v[44:45], v[60:61], 0, v[44:45]
	s_waitcnt lgkmcnt(6)
	v_cvt_pk_bf16_f32 v40, v46, v48
	s_waitcnt lgkmcnt(4)
	v_cvt_pk_bf16_f32 v41, v50, v52
	s_waitcnt lgkmcnt(2)
	v_cvt_pk_bf16_f32 v42, v54, v56
	s_waitcnt lgkmcnt(0)
	v_cvt_pk_bf16_f32 v43, v58, v62
	global_store_dwordx4 v[44:45], v[40:43], off
	v_add_u32_e32 v44, s43, v177
	v_ashrrev_i32_e32 v45, 31, v44
	v_lshlrev_b64 v[44:45], 11, v[44:45]
	v_lshl_add_u64 v[44:45], v[60:61], 0, v[44:45]
	v_cvt_pk_bf16_f32 v40, v47, v49
	v_cvt_pk_bf16_f32 v41, v51, v53
	v_cvt_pk_bf16_f32 v42, v55, v57
	v_cvt_pk_bf16_f32 v43, v59, v63
	global_store_dwordx4 v[44:45], v[40:43], off
	s_waitcnt lgkmcnt(0)

.LBB0_186:
	s_andn2_b64 vcc, exec, s[0:1]
	s_cbranch_vccnz .LBB0_23
	s_ashr_i32 s0, s42, 31
	s_lshr_b32 s0, s0, 28
	s_add_i32 s0, s42, s0
	s_ashr_i32 s1, s0, 4
	s_lshl_b32 s34, s1, 5
	s_lshl_b32 s43, s1, 10
	s_and_b32 s1, s34, 0xe0
	s_and_b32 s0, s0, 0xffffff80
	s_or_b32 s52, s0, s1
	s_add_i32 s0, s1, s0
	s_addk_i32 s0, 0xa80
	s_cmpk_lt_u32 s1, 0x80
	s_cselect_b32 s0, s52, s0
	s_ashr_i32 s1, s0, 31
	v_lshl_add_u64 v[40:41], s[0:1], 2, v[20:21]
	s_sub_i32 s0, s4, s43
	v_add_u32_e32 v42, s0, v65
	v_mov_b32_e32 v232, v42
	v_ashrrev_i32_e32 v233, 31, v232
	v_lshl_add_u64 v[238:239], v[232:233], 2, s[18:19]
	v_and_b32_e32 v237, 31, v64
	v_mul_u32_u24_e32 v236, 33, v65
	v_add_lshl_u32 v236, v236, v237, 2
	s_lshl_b32 s99, s33, 14
	v_add_u32_e32 v236, s99, v236
	v_mad_i64_i32 v[234:235], s[100:101], v232, s23, v[40:41]
	global_load_dword v200, v[234:235], off
	v_add_u32_e32 v232, 2, v232
	v_mad_i64_i32 v[234:235], s[100:101], v232, s23, v[40:41]
	global_load_dword v201, v[234:235], off
	v_add_u32_e32 v232, 2, v232
	v_mad_i64_i32 v[234:235], s[100:101], v232, s23, v[40:41]
	global_load_dword v202, v[234:235], off
	v_add_u32_e32 v232, 2, v232
	v_mad_i64_i32 v[234:235], s[100:101], v232, s23, v[40:41]
	global_load_dword v203, v[234:235], off
	v_add_u32_e32 v232, 2, v232
	v_mad_i64_i32 v[234:235], s[100:101], v232, s23, v[40:41]
	global_load_dword v204, v[234:235], off
	v_add_u32_e32 v232, 2, v232
	v_mad_i64_i32 v[234:235], s[100:101], v232, s23, v[40:41]
	global_load_dword v205, v[234:235], off
	v_add_u32_e32 v232, 2, v232
	v_mad_i64_i32 v[234:235], s[100:101], v232, s23, v[40:41]
	global_load_dword v206, v[234:235], off
	v_add_u32_e32 v232, 2, v232
	v_mad_i64_i32 v[234:235], s[100:101], v232, s23, v[40:41]
	global_load_dword v207, v[234:235], off
	v_add_u32_e32 v232, 2, v232
	v_mad_i64_i32 v[234:235], s[100:101], v232, s23, v[40:41]
	global_load_dword v208, v[234:235], off
	v_add_u32_e32 v232, 2, v232
	v_mad_i64_i32 v[234:235], s[100:101], v232, s23, v[40:41]
	global_load_dword v209, v[234:235], off
	v_add_u32_e32 v232, 2, v232
	v_mad_i64_i32 v[234:235], s[100:101], v232, s23, v[40:41]
	global_load_dword v210, v[234:235], off
	v_add_u32_e32 v232, 2, v232
	v_mad_i64_i32 v[234:235], s[100:101], v232, s23, v[40:41]
	global_load_dword v211, v[234:235], off
	v_add_u32_e32 v232, 2, v232
	v_mad_i64_i32 v[234:235], s[100:101], v232, s23, v[40:41]
	global_load_dword v212, v[234:235], off
	v_add_u32_e32 v232, 2, v232
	v_mad_i64_i32 v[234:235], s[100:101], v232, s23, v[40:41]
	global_load_dword v213, v[234:235], off
	v_add_u32_e32 v232, 2, v232
	v_mad_i64_i32 v[234:235], s[100:101], v232, s23, v[40:41]
	global_load_dword v214, v[234:235], off
	v_add_u32_e32 v232, 2, v232
	v_mad_i64_i32 v[234:235], s[100:101], v232, s23, v[40:41]
	global_load_dword v215, v[234:235], off
	v_add_u32_e32 v232, 2, v232
	global_load_dword v216, v[238:239], off offset:0
	global_load_dword v217, v[238:239], off offset:8
	global_load_dword v218, v[238:239], off offset:16
	global_load_dword v219, v[238:239], off offset:24
	global_load_dword v220, v[238:239], off offset:32
	global_load_dword v221, v[238:239], off offset:40
	global_load_dword v222, v[238:239], off offset:48
	global_load_dword v223, v[238:239], off offset:56
	global_load_dword v224, v[238:239], off offset:64
	global_load_dword v225, v[238:239], off offset:72
	global_load_dword v226, v[238:239], off offset:80
	global_load_dword v227, v[238:239], off offset:88
	global_load_dword v228, v[238:239], off offset:96
	global_load_dword v229, v[238:239], off offset:104
	global_load_dword v230, v[238:239], off offset:112
	global_load_dword v231, v[238:239], off offset:120
	s_waitcnt vmcnt(0)
	v_mul_f32_e32 v200, v200, v216
	v_mul_f32_e32 v201, v201, v217
	v_mul_f32_e32 v202, v202, v218
	v_mul_f32_e32 v203, v203, v219
	v_mul_f32_e32 v204, v204, v220
	v_mul_f32_e32 v205, v205, v221
	v_mul_f32_e32 v206, v206, v222
	v_mul_f32_e32 v207, v207, v223
	v_mul_f32_e32 v208, v208, v224
	v_mul_f32_e32 v209, v209, v225
	v_mul_f32_e32 v210, v210, v226
	v_mul_f32_e32 v211, v211, v227
	v_mul_f32_e32 v212, v212, v228
	v_mul_f32_e32 v213, v213, v229
	v_mul_f32_e32 v214, v214, v230
	v_mul_f32_e32 v215, v215, v231
	ds_write_b32 v236, v200 offset:0
	ds_write_b32 v236, v201 offset:264
	ds_write_b32 v236, v202 offset:528
	ds_write_b32 v236, v203 offset:792
	ds_write_b32 v236, v204 offset:1056
	ds_write_b32 v236, v205 offset:1320
	ds_write_b32 v236, v206 offset:1584
	ds_write_b32 v236, v207 offset:1848
	ds_write_b32 v236, v208 offset:2112
	ds_write_b32 v236, v209 offset:2376
	ds_write_b32 v236, v210 offset:2640
	ds_write_b32 v236, v211 offset:2904
	ds_write_b32 v236, v212 offset:3168
	ds_write_b32 v236, v213 offset:3432
	ds_write_b32 v236, v214 offset:3696
	ds_write_b32 v236, v215 offset:3960
	v_mad_i64_i32 v[234:235], s[100:101], v232, s23, v[40:41]
	global_load_dword v200, v[234:235], off
	v_add_u32_e32 v232, 2, v232
	v_mad_i64_i32 v[234:235], s[100:101], v232, s23, v[40:41]
	global_load_dword v201, v[234:235], off
	v_add_u32_e32 v232, 2, v232
	v_mad_i64_i32 v[234:235], s[100:101], v232, s23, v[40:41]
	global_load_dword v202, v[234:235], off
	v_add_u32_e32 v232, 2, v232
	v_mad_i64_i32 v[234:235], s[100:101], v232, s23, v[40:41]
	global_load_dword v203, v[234:235], off
	v_add_u32_e32 v232, 2, v232
	v_mad_i64_i32 v[234:235], s[100:101], v232, s23, v[40:41]
	global_load_dword v204, v[234:235], off
	v_add_u32_e32 v232, 2, v232
	v_mad_i64_i32 v[234:235], s[100:101], v232, s23, v[40:41]
	global_load_dword v205, v[234:235], off
	v_add_u32_e32 v232, 2, v232
	v_mad_i64_i32 v[234:235], s[100:101], v232, s23, v[40:41]
	global_load_dword v206, v[234:235], off
	v_add_u32_e32 v232, 2, v232
	v_mad_i64_i32 v[234:235], s[100:101], v232, s23, v[40:41]
	global_load_dword v207, v[234:235], off
	v_add_u32_e32 v232, 2, v232
	v_mad_i64_i32 v[234:235], s[100:101], v232, s23, v[40:41]
	global_load_dword v208, v[234:235], off
	v_add_u32_e32 v232, 2, v232
	v_mad_i64_i32 v[234:235], s[100:101], v232, s23, v[40:41]
	global_load_dword v209, v[234:235], off
	v_add_u32_e32 v232, 2, v232
	v_mad_i64_i32 v[234:235], s[100:101], v232, s23, v[40:41]
	global_load_dword v210, v[234:235], off
	v_add_u32_e32 v232, 2, v232
	v_mad_i64_i32 v[234:235], s[100:101], v232, s23, v[40:41]
	global_load_dword v211, v[234:235], off
	v_add_u32_e32 v232, 2, v232
	v_mad_i64_i32 v[234:235], s[100:101], v232, s23, v[40:41]
	global_load_dword v212, v[234:235], off
	v_add_u32_e32 v232, 2, v232
	v_mad_i64_i32 v[234:235], s[100:101], v232, s23, v[40:41]
	global_load_dword v213, v[234:235], off
	v_add_u32_e32 v232, 2, v232
	v_mad_i64_i32 v[234:235], s[100:101], v232, s23, v[40:41]
	global_load_dword v214, v[234:235], off
	v_add_u32_e32 v232, 2, v232
	v_mad_i64_i32 v[234:235], s[100:101], v232, s23, v[40:41]
	global_load_dword v215, v[234:235], off
	v_add_u32_e32 v232, 2, v232
	global_load_dword v216, v[238:239], off offset:128
	global_load_dword v217, v[238:239], off offset:136
	global_load_dword v218, v[238:239], off offset:144
	global_load_dword v219, v[238:239], off offset:152
	global_load_dword v220, v[238:239], off offset:160
	global_load_dword v221, v[238:239], off offset:168
	global_load_dword v222, v[238:239], off offset:176
	global_load_dword v223, v[238:239], off offset:184
	global_load_dword v224, v[238:239], off offset:192
	global_load_dword v225, v[238:239], off offset:200
	global_load_dword v226, v[238:239], off offset:208
	global_load_dword v227, v[238:239], off offset:216
	global_load_dword v228, v[238:239], off offset:224
	global_load_dword v229, v[238:239], off offset:232
	global_load_dword v230, v[238:239], off offset:240
	global_load_dword v231, v[238:239], off offset:248
	s_waitcnt vmcnt(0)
	v_mul_f32_e32 v200, v200, v216
	v_mul_f32_e32 v201, v201, v217
	v_mul_f32_e32 v202, v202, v218
	v_mul_f32_e32 v203, v203, v219
	v_mul_f32_e32 v204, v204, v220
	v_mul_f32_e32 v205, v205, v221
	v_mul_f32_e32 v206, v206, v222
	v_mul_f32_e32 v207, v207, v223
	v_mul_f32_e32 v208, v208, v224
	v_mul_f32_e32 v209, v209, v225
	v_mul_f32_e32 v210, v210, v226
	v_mul_f32_e32 v211, v211, v227
	v_mul_f32_e32 v212, v212, v228
	v_mul_f32_e32 v213, v213, v229
	v_mul_f32_e32 v214, v214, v230
	v_mul_f32_e32 v215, v215, v231
	ds_write_b32 v236, v200 offset:4224
	ds_write_b32 v236, v201 offset:4488
	ds_write_b32 v236, v202 offset:4752
	ds_write_b32 v236, v203 offset:5016
	ds_write_b32 v236, v204 offset:5280
	ds_write_b32 v236, v205 offset:5544
	ds_write_b32 v236, v206 offset:5808
	ds_write_b32 v236, v207 offset:6072
	ds_write_b32 v236, v208 offset:6336
	ds_write_b32 v236, v209 offset:6600
	ds_write_b32 v236, v210 offset:6864
	ds_write_b32 v236, v211 offset:7128
	ds_write_b32 v236, v212 offset:7392
	ds_write_b32 v236, v213 offset:7656
	ds_write_b32 v236, v214 offset:7920
	ds_write_b32 v236, v215 offset:8184
	s_branch .LBB0_22

	.amdhsa_kernel _Z4mega4Args
		.amdhsa_group_segment_fixed_size 0
		.amdhsa_private_segment_fixed_size 0
		.amdhsa_kernarg_size 576
		.amdhsa_user_sgpr_count 2
		.amdhsa_user_sgpr_dispatch_ptr 0
		.amdhsa_user_sgpr_queue_ptr 0
		.amdhsa_user_sgpr_kernarg_segment_ptr 1
		.amdhsa_user_sgpr_dispatch_id 0
		.amdhsa_user_sgpr_kernarg_preload_length 0
		.amdhsa_user_sgpr_kernarg_preload_offset 0
		.amdhsa_user_sgpr_private_segment_size 0
		.amdhsa_uses_dynamic_stack 0
		.amdhsa_enable_private_segment 0
		.amdhsa_system_sgpr_workgroup_id_x 1
		.amdhsa_system_sgpr_workgroup_id_y 0
		.amdhsa_system_sgpr_workgroup_id_z 0
		.amdhsa_system_sgpr_workgroup_info 0
		.amdhsa_system_vgpr_workitem_id 2
		.amdhsa_next_free_vgpr 256
		.amdhsa_next_free_sgpr 102
		.amdhsa_accum_offset 256
		.amdhsa_reserve_vcc 1
		.amdhsa_float_round_mode_32 0
		.amdhsa_float_round_mode_16_64 0
		.amdhsa_float_denorm_mode_32 3
		.amdhsa_float_denorm_mode_16_64 3
		.amdhsa_dx10_clamp 1
		.amdhsa_ieee_mode 1
		.amdhsa_fp16_overflow 0
		.amdhsa_tg_split 0
		.amdhsa_exception_fp_ieee_invalid_op 0
		.amdhsa_exception_fp_denorm_src 0
		.amdhsa_exception_fp_ieee_div_zero 0
		.amdhsa_exception_fp_ieee_overflow 0
		.amdhsa_exception_fp_ieee_underflow 0
		.amdhsa_exception_fp_ieee_inexact 0
		.amdhsa_exception_int_div_zero 0
	.end_amdhsa_kernel
